# v35 + sliding-window attention loop: 30 plain v_pk_mul_f32 replaced by scalar v_mul_f32 pairs
# baseline (speedup 1.0000x reference)
; __device__ __forceinline__ float bflo(unsigned w) { return __uint_as_float(w << 16); }
; __device__ __forceinline__ float bfhi(unsigned w) { return __uint_as_float(w & 0xffff0000u); }
; __device__ __forceinline__ float half_sum(float x) { const HalfPair p = half_swap(x); return p.a + p.b; }
; __device__ __forceinline__ void swa_mfma(const Params& P, int li, const bf16_t* __restrict__ proj, bf16_t* __restrict__ mix, LAS unsigned char* ldsl) {
;     ...
;     for (int unit = gw; unit < BATCH * 8 * 128; unit += ngw) {
;         const int g = unit & 127, hq = (unit >> 7) & 7, b = unit >> 10, kvh = hq >> 2;
;         const size_t rowb = (size_t)b * SEQ;
;         const int t0 = g * 32;
;         const float sink2 = P.in[5][li * 8 + hq] * LOG2E;
;         const bf16_t* kbase = proj + rowb * 1280 + 512 + kvh * 64;
;         u32x4 stg[4], qraw[4];
;         tile_load_nt(qraw, proj + (rowb + t0) * 1280 + hq * 64, 1280, lane);
;         { const int kb0 = t0 - 128; tile_load(stg, kbase + (size_t)(kb0 < 0 ? 0 : kb0) * 1280, 1280, lane); }
;         tile_to_lds(kimg, qraw, lane);
;         frag_read(qraw, kimg, r32, hi);
;         u32x4 qf[4];
;         {
;             float qv[32]; float ss = 0.f;
; #pragma unroll
;             for (int d0 = 0; d0 < 4; ++d0) { const u32x4 w = qraw[d0];
;                 qv[8 * d0 + 0] = bflo(w.x); qv[8 * d0 + 1] = bfhi(w.x); qv[8 * d0 + 2] = bflo(w.y); qv[8 * d0 + 3] = bfhi(w.y);
;                 qv[8 * d0 + 4] = bflo(w.z); qv[8 * d0 + 5] = bfhi(w.z); qv[8 * d0 + 6] = bflo(w.w); qv[8 * d0 + 7] = bfhi(w.w); }
; #pragma unroll
;             for (int i = 0; i < 32; ++i) ss += qv[i] * qv[i];
;             ss = half_sum(ss);
;             const float sc = __builtin_amdgcn_rsqf(ss * (1.f / 64.f) + EPS) * (0.125f * LOG2E);
.LBB0_214:
	s_bfe_u32 s58, s65, 0x30007
	s_ashr_i32 s36, s65, 10
	s_mov_b32 s50, s68
	s_ashr_i32 s37, s36, 31
	s_mov_b32 s41, s57
	s_or_b32 s40, s58, s66
	v_readlane_b32 s68, v227, 0
	s_lshl_b64 s[44:45], s[36:37], 12
	s_and_b32 s48, s67, 0xfe0
	s_lshl_b64 s[40:41], s[40:41], 2
	v_readlane_b32 s78, v227, 10
	v_readlane_b32 s79, v227, 11
	s_add_u32 s40, s78, s40
	s_addc_u32 s41, s79, s41
	s_mul_hi_i32 s37, s36, 0xa00000
	s_mul_i32 s36, s36, 0xa00000
	s_add_u32 s36, s98, s36
	s_addc_u32 s37, s99, s37
	s_lshr_b32 s46, s65, 2
	s_and_b32 s46, s46, 0x80
	s_add_u32 s36, s36, s46
	s_addc_u32 s37, s37, 0
	s_or_b32 s44, s44, s48
	s_mul_i32 s46, s45, 0xa00
	s_mul_hi_u32 s47, s44, 0xa00
	s_add_i32 s47, s47, s46
	s_mul_i32 s46, s44, 0xa00
	s_add_u32 s46, s98, s46
	s_addc_u32 s47, s99, s47
	s_lshl_b32 s49, s58, 7
	s_add_u32 s46, s46, s49
	s_addc_u32 s47, s47, 0
	v_lshl_add_u64 v[0:1], s[46:47], 0, v[112:113]
	v_lshl_add_u64 v[0:1], v[0:1], 0, v[114:115]
	s_movk_i32 s49, 0x5000
	v_add_co_u32_e32 v2, vcc, s49, v0
	s_mov_b32 s51, 0xa000
	s_nop 0
	v_addc_co_u32_e32 v3, vcc, 0, v1, vcc
	v_add_co_u32_e32 v4, vcc, s51, v0
	global_load_dwordx4 v[8:11], v[0:1], off nt
	s_nop 0
	v_addc_co_u32_e32 v5, vcc, 0, v1, vcc
	global_load_dwordx4 v[12:15], v[2:3], off nt
	global_load_dwordx4 v[16:19], v[4:5], off nt
	s_mov_b32 s68, 0xf000
	v_add_co_u32_e32 v0, vcc, s68, v0
	v_mov_b32_e32 v146, 0xff800000
	s_nop 0
	v_addc_co_u32_e32 v1, vcc, 0, v1, vcc
	global_load_dwordx4 v[20:23], v[0:1], off nt
	global_load_dwordx4 v[24:27], v[108:109], off offset:16
	global_load_dwordx4 v[28:31], v[108:109], off
	global_load_dwordx4 v[32:35], v[110:111], off offset:16
	global_load_dwordx4 v[36:39], v[110:111], off
	global_load_dword v78, v149, s[40:41]
	s_add_i32 s40, s48, 0xffffff80
	s_max_i32 s41, s40, 0
	s_mulk_i32 s41, 0xa00
	s_add_u32 s46, s36, s41
	s_addc_u32 s47, s37, 0
	v_lshl_add_u64 v[0:1], s[46:47], 0, v[112:113]
	v_lshl_add_u64 v[74:75], v[0:1], 0, v[114:115]
	v_add_co_u32_e32 v68, vcc, s49, v74
	global_load_dwordx4 v[0:3], v[74:75], off offset:1024
	s_nop 0
	v_addc_co_u32_e32 v69, vcc, 0, v75, vcc
	global_load_dwordx4 v[4:7], v[68:69], off offset:1024
	v_add_co_u32_e32 v70, vcc, s51, v74
	v_mov_b32_e32 v145, 0xff800000
	s_nop 0
	v_addc_co_u32_e32 v71, vcc, 0, v75, vcc
	v_add_co_u32_e32 v72, vcc, s68, v74
	v_mov_b32_e32 v144, 0xff800000
	s_nop 0
	v_addc_co_u32_e32 v73, vcc, 0, v75, vcc
	v_mov_b32_e32 v143, 0xff800000
	v_mov_b32_e32 v142, 0xff800000
	v_mov_b32_e32 v141, 0xff800000
	v_mov_b32_e32 v140, 0xff800000
	v_mov_b32_e32 v139, 0xff800000
	v_mov_b32_e32 v138, 0xff800000
	v_mov_b32_e32 v137, 0xff800000
	v_mov_b32_e32 v136, 0xff800000
	v_mov_b32_e32 v135, 0xff800000
	v_mov_b32_e32 v134, 0xff800000
	v_mov_b32_e32 v133, 0xff800000
	v_mov_b32_e32 v119, 0xff800000
	s_waitcnt vmcnt(15)
	v_mov_b32_e32 v117, 0xff800000
	v_readlane_b32 s69, v227, 1
	v_readlane_b32 s70, v227, 2
	v_readlane_b32 s71, v227, 3
	v_readlane_b32 s72, v227, 4
	v_readlane_b32 s73, v227, 5
	v_readlane_b32 s74, v227, 6
	v_readlane_b32 s75, v227, 7
	v_readlane_b32 s76, v227, 8
	v_readlane_b32 s77, v227, 9
	v_readlane_b32 s80, v227, 12
	v_readlane_b32 s81, v227, 13
	v_readlane_b32 s82, v227, 14
	s_waitcnt vmcnt(10)
	ds_write_b128 v128, v[8:11]
	s_waitcnt vmcnt(9)
	ds_write_b128 v128, v[12:15] offset:1152
	s_waitcnt vmcnt(8)
	ds_write_b128 v128, v[16:19] offset:2304
	s_waitcnt vmcnt(7)
	ds_write_b128 v128, v[20:23] offset:3456
	ds_read_b128 v[8:11], v129
	ds_read_b128 v[12:15], v129 offset:32
	ds_read_b128 v[16:19], v129 offset:64
	ds_read_b128 v[20:23], v129 offset:96
	v_readlane_b32 s83, v227, 15
	s_waitcnt lgkmcnt(2)
	v_lshlrev_b32_e32 v48, 16, v12
	v_and_b32_e32 v41, 0xffff0000, v8
	v_lshlrev_b32_e32 v40, 16, v8
	v_mul_f32_e32 v8, v41, v41
	v_lshlrev_b32_e32 v42, 16, v9
	v_fmac_f32_e32 v8, v40, v40
	v_and_b32_e32 v43, 0xffff0000, v9
	v_fmac_f32_e32 v8, v42, v42
	v_lshlrev_b32_e32 v44, 16, v10
	v_fmac_f32_e32 v8, v43, v43
	v_and_b32_e32 v45, 0xffff0000, v10
	v_fmac_f32_e32 v8, v44, v44
	v_lshlrev_b32_e32 v46, 16, v11
	v_fmac_f32_e32 v8, v45, v45
	v_and_b32_e32 v47, 0xffff0000, v11
	v_fmac_f32_e32 v8, v46, v46
	v_fmac_f32_e32 v8, v47, v47
	v_and_b32_e32 v49, 0xffff0000, v12
	v_fmac_f32_e32 v8, v48, v48
	v_lshlrev_b32_e32 v50, 16, v13
	v_fmac_f32_e32 v8, v49, v49
	v_and_b32_e32 v51, 0xffff0000, v13
	v_fmac_f32_e32 v8, v50, v50
	v_lshlrev_b32_e32 v52, 16, v14
	v_fmac_f32_e32 v8, v51, v51
	v_and_b32_e32 v53, 0xffff0000, v14
	v_fmac_f32_e32 v8, v52, v52
	v_lshlrev_b32_e32 v54, 16, v15
	v_fmac_f32_e32 v8, v53, v53
	v_and_b32_e32 v55, 0xffff0000, v15
	v_fmac_f32_e32 v8, v54, v54
	s_waitcnt lgkmcnt(1)
	v_lshlrev_b32_e32 v56, 16, v16
	v_fmac_f32_e32 v8, v55, v55
	v_and_b32_e32 v57, 0xffff0000, v16
	v_fmac_f32_e32 v8, v56, v56
	v_lshlrev_b32_e32 v58, 16, v17
	v_fmac_f32_e32 v8, v57, v57
	v_and_b32_e32 v59, 0xffff0000, v17
	v_fmac_f32_e32 v8, v58, v58
	v_lshlrev_b32_e32 v60, 16, v18
	v_fmac_f32_e32 v8, v59, v59
	v_and_b32_e32 v61, 0xffff0000, v18
	v_fmac_f32_e32 v8, v60, v60
	v_lshlrev_b32_e32 v62, 16, v19
	v_fmac_f32_e32 v8, v61, v61
	v_and_b32_e32 v63, 0xffff0000, v19
	v_fmac_f32_e32 v8, v62, v62
	s_waitcnt lgkmcnt(0)
	v_lshlrev_b32_e32 v79, 16, v20
	v_fmac_f32_e32 v8, v63, v63
	v_and_b32_e32 v88, 0xffff0000, v20
	v_fmac_f32_e32 v8, v79, v79
	v_lshlrev_b32_e32 v89, 16, v21
	v_fmac_f32_e32 v8, v88, v88
	v_and_b32_e32 v90, 0xffff0000, v21
	v_fmac_f32_e32 v8, v89, v89
	v_lshlrev_b32_e32 v91, 16, v22
	v_fmac_f32_e32 v8, v90, v90
	v_and_b32_e32 v92, 0xffff0000, v22
	v_fmac_f32_e32 v8, v91, v91
	v_lshlrev_b32_e32 v93, 16, v23
	v_fmac_f32_e32 v8, v92, v92
	v_and_b32_e32 v94, 0xffff0000, v23
	v_fmac_f32_e32 v8, v93, v93
	v_fmac_f32_e32 v8, v94, v94
	v_mov_b32_e32 v9, v8
	s_nop 1
	v_permlane32_swap_b32_e32 v8, v9
	v_add_f32_e32 v8, v8, v9
	v_fmamk_f32 v8, v8, 0x3c800000, v185
	v_rsq_f32_e32 v16, v8
	global_load_dwordx4 v[8:11], v[70:71], off offset:1024
	global_load_dwordx4 v[12:15], v[72:73], off offset:1024
	v_mul_f32_e32 v95, 0x3e38aa3b, v16
	v_mul_f32_e32 v16, v95, v40
	v_mul_f32_e32 v17, v95, v41
	s_waitcnt vmcnt(7)
; __device__ __forceinline__ unsigned pk2(float lo, float hi) { return pg8::cvt_pk_bf16(lo, hi); }
; __device__ __forceinline__ void swa_mfma(const Params& P, int li, const bf16_t* __restrict__ proj, bf16_t* __restrict__ mix, LAS unsigned char* ldsl) {
;     ...
;             const float sc = __builtin_amdgcn_rsqf(ss * (1.f / 64.f) + EPS) * (0.125f * LOG2E);
; #pragma unroll
;             for (int d0 = 0; d0 < 4; ++d0) {
;                 const f32x4 g0 = *(const f32x4*)(qn + 16 * d0 + 8 * hi), g1 = *(const f32x4*)(qn + 16 * d0 + 8 * hi + 4);
;                 const f32x4 k0 = *(const f32x4*)(kn + 16 * d0 + 8 * hi), k1 = *(const f32x4*)(kn + 16 * d0 + 8 * hi + 4);
;                 u32x4 w;
;                 w.x = pk2(qv[8 * d0 + 0] * sc * g0[0] * k0[0], qv[8 * d0 + 1] * sc * g0[1] * k0[1]);
;                 w.y = pk2(qv[8 * d0 + 2] * sc * g0[2] * k0[2], qv[8 * d0 + 3] * sc * g0[3] * k0[3]);
;                 w.z = pk2(qv[8 * d0 + 4] * sc * g1[0] * k1[0], qv[8 * d0 + 5] * sc * g1[1] * k1[1]);
;                 w.w = pk2(qv[8 * d0 + 6] * sc * g1[2] * k1[2], qv[8 * d0 + 7] * sc * g1[3] * k1[3]);
;                 qf[d0] = w;
;             }
;         }
;         f32x16 s[5];
; #pragma unroll
;         for (int j = 0; j < 5; ++j) {
;             const int kb = t0 - 128 + 32 * j;
;             tile_to_lds(kimg, stg, lane);
;             if (j < 4) { const int kn1 = kb + 32; tile_load(stg, kbase + (size_t)(kn1 < 0 ? 0 : kn1) * 1280, 1280, lane); }
	v_mul_f32_e32 v16, v28, v16
	v_mul_f32_e32 v17, v29, v17
	s_waitcnt vmcnt(5)
	v_mul_f32_e32 v16, v36, v16
	v_mul_f32_e32 v17, v37, v17
	v_cvt_pk_bf16_f32 v64, v16, v17
	v_mul_f32_e32 v16, v95, v42
	v_mul_f32_e32 v17, v95, v43
	v_mul_f32_e32 v16, v30, v16
	v_mul_f32_e32 v17, v31, v17
	v_mul_f32_e32 v16, v38, v16
	v_mul_f32_e32 v17, v39, v17
	v_cvt_pk_bf16_f32 v65, v16, v17
	v_mul_f32_e32 v16, v95, v44
	v_mul_f32_e32 v17, v95, v45
	v_mul_f32_e32 v16, v24, v16
	v_mul_f32_e32 v17, v25, v17
	v_mul_f32_e32 v16, v32, v16
	v_mul_f32_e32 v17, v33, v17
	v_cvt_pk_bf16_f32 v66, v16, v17
	v_mul_f32_e32 v16, v95, v46
	v_mul_f32_e32 v17, v95, v47
	v_mul_f32_e32 v16, v26, v16
	v_mul_f32_e32 v17, v27, v17
	v_mul_f32_e32 v16, v34, v16
	v_mul_f32_e32 v17, v35, v17
	v_cvt_pk_bf16_f32 v67, v16, v17
	global_load_dwordx4 v[16:19], v[108:109], off offset:64
	global_load_dwordx4 v[20:23], v[108:109], off offset:80
	global_load_dwordx4 v[24:27], v[110:111], off offset:64
	global_load_dwordx4 v[28:31], v[110:111], off offset:80
	v_mul_f32_e32 v32, v95, v48
	v_mul_f32_e32 v33, v95, v49
	v_mul_f32_e32 v34, v95, v50
	v_mul_f32_e32 v35, v95, v51
	v_mul_f32_e32 v36, v95, v52
	v_mul_f32_e32 v37, v95, v53
	v_mul_f32_e32 v38, v95, v54
	v_mul_f32_e32 v39, v95, v55
	v_mul_f32_e32 v40, v95, v89
	v_mul_f32_e32 v41, v95, v90
	v_mul_f32_e32 v42, v95, v91
	v_mul_f32_e32 v43, v95, v92
	v_mul_f32_e32 v44, v95, v93
	v_mul_f32_e32 v45, v95, v94
	s_waitcnt vmcnt(3)
	v_mul_f32_e32 v16, v32, v16
	v_mul_f32_e32 v17, v33, v17
	v_mul_f32_e32 v18, v34, v18
	v_mul_f32_e32 v19, v35, v19
	s_waitcnt vmcnt(2)
	v_mul_f32_e32 v20, v36, v20
	v_mul_f32_e32 v21, v37, v21
	v_mul_f32_e32 v22, v38, v22
	v_mul_f32_e32 v23, v39, v23
	s_waitcnt vmcnt(1)
	v_mul_f32_e32 v16, v16, v24
	v_mul_f32_e32 v17, v17, v25
	v_mul_f32_e32 v18, v18, v26
	v_mul_f32_e32 v19, v19, v27
	s_waitcnt vmcnt(0)
	v_mul_f32_e32 v20, v20, v28
	v_mul_f32_e32 v21, v21, v29
	v_mul_f32_e32 v22, v22, v30
	v_mul_f32_e32 v23, v23, v31
	v_cvt_pk_bf16_f32 v80, v16, v17
	v_cvt_pk_bf16_f32 v81, v18, v19
	v_cvt_pk_bf16_f32 v82, v20, v21
	v_cvt_pk_bf16_f32 v83, v22, v23
	global_load_dwordx4 v[16:19], v[108:109], off offset:128
	global_load_dwordx4 v[20:23], v[108:109], off offset:144
	global_load_dwordx4 v[24:27], v[110:111], off offset:128
	global_load_dwordx4 v[28:31], v[110:111], off offset:144
	v_mul_f32_e32 v32, v95, v56
	v_mul_f32_e32 v33, v95, v57
	v_mul_f32_e32 v34, v95, v58
	v_mul_f32_e32 v35, v95, v59
	v_mul_f32_e32 v36, v95, v60
	v_mul_f32_e32 v37, v95, v61
	v_mul_f32_e32 v38, v95, v62
	v_mul_f32_e32 v39, v95, v63
	s_waitcnt vmcnt(3)
	v_mul_f32_e32 v16, v32, v16
	v_mul_f32_e32 v17, v33, v17
	v_mul_f32_e32 v18, v34, v18
	v_mul_f32_e32 v19, v35, v19
	s_waitcnt vmcnt(2)
	v_mul_f32_e32 v20, v36, v20
	v_mul_f32_e32 v21, v37, v21
	v_mul_f32_e32 v22, v38, v22
	v_mul_f32_e32 v23, v39, v23
	s_waitcnt vmcnt(1)
	v_mul_f32_e32 v16, v16, v24
	v_mul_f32_e32 v17, v17, v25
	v_mul_f32_e32 v18, v18, v26
	v_mul_f32_e32 v19, v19, v27
	s_waitcnt vmcnt(0)
	v_mul_f32_e32 v20, v20, v28
	v_mul_f32_e32 v21, v21, v29
	v_mul_f32_e32 v22, v22, v30
	v_mul_f32_e32 v23, v23, v31
	v_cvt_pk_bf16_f32 v84, v16, v17
	v_cvt_pk_bf16_f32 v85, v18, v19
	v_cvt_pk_bf16_f32 v86, v20, v21
	v_cvt_pk_bf16_f32 v87, v22, v23
	global_load_dwordx4 v[16:19], v[108:109], off offset:192
	global_load_dwordx4 v[20:23], v[108:109], off offset:208
	global_load_dwordx4 v[24:27], v[110:111], off offset:192
	global_load_dwordx4 v[28:31], v[110:111], off offset:208
	v_lshl_add_u64 v[32:33], s[36:37], 0, v[112:113]
	s_max_i32 s36, s40, 0xffffffe0
	v_lshl_add_u64 v[76:77], v[32:33], 0, v[114:115]
	s_add_i32 s36, s36, 32
	v_mad_u64_u32 v[120:121], s[36:37], s36, v192, v[76:77]
	v_add_co_u32_e32 v32, vcc, s49, v120
	s_mov_b64 s[36:37], vcc
	v_add_co_u32_e32 v34, vcc, 0xa000, v120
	v_addc_co_u32_e64 v33, s[36:37], 0, v121, s[36:37]
	s_mov_b64 s[36:37], vcc
	v_mul_f32_e32 v38, v95, v79
	v_mul_f32_e32 v39, v95, v88
	v_add_co_u32_e32 v36, vcc, 0xf000, v120
	v_addc_co_u32_e64 v35, s[36:37], 0, v121, s[36:37]
	s_nop 0
	v_addc_co_u32_e32 v37, vcc, 0, v121, vcc
	s_cmpk_gt_u32 s48, 0x7f
	s_cselect_b64 s[36:37], -1, 0
	s_cmpk_lt_u32 s48, 0x80
	s_waitcnt vmcnt(3)
	v_mul_f32_e32 v16, v38, v16
	v_mul_f32_e32 v17, v39, v17
	v_mul_f32_e32 v18, v40, v18
	v_mul_f32_e32 v19, v41, v19
	s_waitcnt vmcnt(2)
	v_mul_f32_e32 v20, v42, v20
	v_mul_f32_e32 v21, v43, v21
	v_mul_f32_e32 v22, v44, v22
	v_mul_f32_e32 v23, v45, v23
	s_waitcnt vmcnt(1)
	v_mul_f32_e32 v16, v16, v24
	v_mul_f32_e32 v17, v17, v25
	v_mul_f32_e32 v18, v18, v26
	v_mul_f32_e32 v19, v19, v27
	s_waitcnt vmcnt(0)
	v_mul_f32_e32 v20, v20, v28
	v_mul_f32_e32 v21, v21, v29
	v_mul_f32_e32 v22, v22, v30
	v_mul_f32_e32 v23, v23, v31
	v_cvt_pk_bf16_f32 v88, v16, v17
	v_cvt_pk_bf16_f32 v89, v18, v19
	v_cvt_pk_bf16_f32 v90, v20, v21
	v_cvt_pk_bf16_f32 v91, v22, v23
	global_load_dwordx4 v[24:27], v[120:121], off offset:1024
	global_load_dwordx4 v[28:31], v[32:33], off offset:1024
	s_nop 0
	global_load_dwordx4 v[32:35], v[34:35], off offset:1024
	s_nop 0
	global_load_dwordx4 v[40:43], v[36:37], off offset:1024
	ds_write_b128 v128, v[0:3]
	ds_write_b128 v128, v[4:7] offset:1152
	ds_write_b128 v128, v[8:11] offset:2304
	ds_write_b128 v128, v[12:15] offset:3456
	v_mov_b32_e32 v0, 0xff800000
	s_cbranch_scc1 .LBB0_216
; __device__ __forceinline__ float bflo(unsigned w) { return __uint_as_float(w << 16); }
; __device__ __forceinline__ float bfhi(unsigned w) { return __uint_as_float(w & 0xffff0000u); }
; __device__ __forceinline__ unsigned pk2(float lo, float hi) { return pg8::cvt_pk_bf16(lo, hi); }
; __device__ __forceinline__ float half_sum(float x) { const HalfPair p = half_swap(x); return p.a + p.b; }
; __device__ __forceinline__ int crow(int r, int hi) { return (r & 3) + 8 * (r >> 2) + 4 * hi; }
; __device__ __forceinline__ void swa_mfma(const Params& P, int li, const bf16_t* __restrict__ proj, bf16_t* __restrict__ mix, LAS unsigned char* ldsl) {
;     ...
; #pragma unroll
;             for (int r = 0; r < 16; ++r) s[j][r] = NEG;
;             if (kb >= 0) {
;                 u32x4 kw[4]; frag_read(kw, kimg, r32, hi);
;                 float kss = 0.f;
; #pragma unroll
;                 for (int d0 = 0; d0 < 4; ++d0) {
;                     const float a0 = bflo(kw[d0].x), a1 = bfhi(kw[d0].x), a2 = bflo(kw[d0].y), a3 = bfhi(kw[d0].y), a4 = bflo(kw[d0].z), a5 = bfhi(kw[d0].z), a6 = bflo(kw[d0].w), a7 = bfhi(kw[d0].w);
;                     kss += (a0 * a0 + a1 * a1) + (a2 * a2 + a3 * a3) + (a4 * a4 + a5 * a5) + (a6 * a6 + a7 * a7); }
;                 kss = half_sum(kss);
;                 const float ksc = __builtin_amdgcn_rsqf(kss * (1.f / 64.f) + EPS);
;                 f32x16 acc;
; #pragma unroll
;                 for (int r = 0; r < 16; ++r) acc[r] = 0.f;
; #pragma unroll
;                 for (int d0 = 0; d0 < 4; ++d0) { u32x4 w;
;                     w.x = pk2(bflo(kw[d0].x) * ksc, bfhi(kw[d0].x) * ksc); w.y = pk2(bflo(kw[d0].y) * ksc, bfhi(kw[d0].y) * ksc);
;                     w.z = pk2(bflo(kw[d0].z) * ksc, bfhi(kw[d0].z) * ksc); w.w = pk2(bflo(kw[d0].w) * ksc, bfhi(kw[d0].w) * ksc);
;                     acc = __builtin_amdgcn_mfma_f32_32x32x16_bf16(as_bf(w), as_bf(qf[d0]), acc, 0, 0, 0); }
; #pragma unroll
;                 for (int r = 0; r < 16; ++r) {
;                     bool valid = true;
;                     if (j == 0) valid = crow(r, hi) > r32;
;                     if (j == 4) valid = crow(r, hi) <= r32;
;                     s[j][r] = valid ? acc[r] : NEG;
;                 }
;             }
	ds_read_b128 v[2:5], v129
	ds_read_b128 v[6:9], v129 offset:32
	ds_read_b128 v[10:13], v129 offset:64
	ds_read_b128 v[14:17], v129 offset:96
	s_waitcnt lgkmcnt(3)
	v_and_b32_e32 v19, 0xffff0000, v3
	s_waitcnt lgkmcnt(2)
	v_lshlrev_b32_e32 v47, 16, v9
	s_waitcnt lgkmcnt(1)
	v_and_b32_e32 v51, 0xffff0000, v10
	v_and_b32_e32 v53, 0xffff0000, v11
	v_lshlrev_b32_e32 v46, 16, v8
	v_and_b32_e32 v49, 0xffff0000, v9
	v_and_b32_e32 v48, 0xffff0000, v8
	v_lshlrev_b32_e32 v50, 16, v10
	v_lshlrev_b32_e32 v52, 16, v11
	s_waitcnt lgkmcnt(0)
	v_lshlrev_b32_e32 v1, 16, v15
	v_and_b32_e32 v79, 0xffff0000, v15
	v_lshlrev_b32_e32 v56, 16, v12
	v_and_b32_e32 v58, 0xffff0000, v12
	v_pk_mov_b32 v[8:9], v[12:13], v[16:17] op_sel:[1,0]
	v_mul_f32_e32 v10, v51, v51
	v_mul_f32_e32 v12, v53, v53
	v_and_b32_e32 v37, 0xffff0000, v2
	v_and_b32_e32 v36, 0xffff0000, v4
	v_mul_f32_e32 v15, v1, v1
	v_mul_f32_e32 v54, v79, v79
	v_and_b32_e32 v59, 0xffff0000, v14
	v_lshlrev_b32_e32 v60, 16, v13
	v_pk_fma_f32 v[10:11], v[50:51], v[50:51], v[10:11] op_sel_hi:[1,1,0]
	v_pk_fma_f32 v[12:13], v[52:53], v[52:53], v[12:13] op_sel_hi:[1,1,0]
	v_lshlrev_b32_e32 v18, 16, v3
	v_mul_f32_e32 v20, v19, v19
	v_lshlrev_b32_e32 v23, 16, v2
	v_lshlrev_b32_e32 v22, 16, v4
	v_mul_f32_e32 v2, v36, v36
	v_mul_f32_e32 v3, v37, v37
	v_lshlrev_b32_e32 v57, 16, v14
	v_and_b32_e32 v63, 0xffff0000, v9
	v_and_b32_e32 v62, 0xffff0000, v8
	v_mul_f32_e32 v8, v58, v58
	v_mul_f32_e32 v9, v59, v59
	v_mov_b32_e32 v11, v15
	v_mov_b32_e32 v13, v54
	v_pk_fma_f32 v[20:21], v[18:19], v[18:19], v[20:21] op_sel_hi:[1,1,0]
	v_pk_fma_f32 v[2:3], v[22:23], v[22:23], v[2:3]
	v_pk_fma_f32 v[8:9], v[56:57], v[56:57], v[8:9]
	v_pk_add_f32 v[10:11], v[10:11], v[12:13]
	v_pk_add_f32 v[20:21], v[2:3], v[20:21] op_sel:[1,0] op_sel_hi:[0,1]
	v_and_b32_e32 v45, 0xffff0000, v7
	v_and_b32_e32 v44, 0xffff0000, v6
	v_lshlrev_b32_e32 v61, 16, v16
	v_pk_add_f32 v[8:9], v[8:9], v[10:11]
	v_mul_f32_e32 v10, v62, v62
	v_mul_f32_e32 v11, v63, v63
	v_pk_add_f32 v[2:3], v[2:3], v[20:21]
	v_lshlrev_b32_e32 v20, 16, v5
	v_and_b32_e32 v21, 0xffff0000, v5
	v_lshlrev_b32_e32 v39, 16, v7
	v_lshlrev_b32_e32 v38, 16, v6
	v_mul_f32_e32 v4, v44, v44
	v_mul_f32_e32 v5, v45, v45
	v_pk_fma_f32 v[10:11], v[60:61], v[60:61], v[10:11]
	v_pk_fma_f32 v[4:5], v[38:39], v[38:39], v[4:5]
	v_mul_f32_e32 v6, v48, v48
	v_mul_f32_e32 v7, v49, v49
	v_pk_add_f32 v[8:9], v[10:11], v[8:9]
	v_mul_f32_e32 v10, v21, v21
	v_pk_add_f32 v[4:5], v[4:5], v[4:5] op_sel:[0,1] op_sel_hi:[1,0]
	v_pk_fma_f32 v[6:7], v[46:47], v[46:47], v[6:7]
	v_lshlrev_b32_e32 v55, 16, v17
	v_pk_fma_f32 v[10:11], v[20:21], v[20:21], v[10:11] op_sel_hi:[1,1,0]
	v_pk_add_f32 v[4:5], v[6:7], v[4:5]
	v_and_b32_e32 v92, 0xffff0000, v17
	v_mov_b32_e32 v54, v10
	v_mov_b32_e32 v12, v2
	v_mov_b32_e32 v13, v55
	v_mul_f32_e32 v93, v92, v92
	v_pk_add_f32 v[2:3], v[10:11], v[2:3]
	v_mul_f32_e32 v10, v54, v12
	v_mul_f32_e32 v11, v55, v13
	v_pk_add_f32 v[4:5], v[6:7], v[4:5] op_sel:[1,0] op_sel_hi:[0,1]
	v_mov_b32_e32 v3, v11
	v_mov_b32_e32 v5, v93
	v_pk_add_f32 v[2:3], v[2:3], v[4:5]
	s_nop 0
	v_pk_add_f32 v[2:3], v[2:3], v[8:9]
	s_nop 0
	v_pk_add_f32 v[2:3], v[2:3], v[2:3] op_sel:[0,1] op_sel_hi:[1,0]
	s_nop 0
	v_mov_b32_e32 v3, v2
	s_nop 1
	v_permlane32_swap_b32_e32 v2, v3
	v_add_f32_e32 v2, v2, v3
	v_fmamk_f32 v2, v2, 0x3c800000, v185
	v_rsq_f32_e32 v54, v2
	s_nop 0
	v_mul_f32_e32 v2, v54, v23
	v_mul_f32_e32 v3, v54, v37
	v_cvt_pk_bf16_f32 v2, v2, v3
	v_mul_f32_e32 v3, v54, v18
	v_mul_f32_e32 v4, v54, v19
	v_cvt_pk_bf16_f32 v3, v3, v4
	v_mul_f32_e32 v4, v54, v22
	v_mul_f32_e32 v5, v54, v36
	v_cvt_pk_bf16_f32 v4, v4, v5
	v_mul_f32_e32 v5, v54, v20
	v_mul_f32_e32 v6, v54, v21
	v_cvt_pk_bf16_f32 v5, v5, v6
	v_mul_f32_e32 v18, v54, v38
	v_mfma_f32_32x32x16_bf16 v[2:17], v[2:5], v[64:67], 0
	v_mul_f32_e32 v19, v54, v44
	v_cvt_pk_bf16_f32 v18, v18, v19
	v_mul_f32_e32 v19, v54, v39
	v_mul_f32_e32 v20, v54, v45
	v_cvt_pk_bf16_f32 v19, v19, v20
	v_mul_f32_e32 v20, v54, v46
	v_mul_f32_e32 v21, v54, v48
	v_cvt_pk_bf16_f32 v20, v20, v21
	v_mul_f32_e32 v21, v54, v47
	v_mul_f32_e32 v22, v54, v49
	v_cvt_pk_bf16_f32 v21, v21, v22
	v_mul_f32_e32 v22, v54, v62
	v_mfma_f32_32x32x16_bf16 v[2:17], v[18:21], v[80:83], v[2:17]
	v_mul_f32_e32 v18, v54, v50
	v_mul_f32_e32 v19, v54, v51
	v_cvt_pk_bf16_f32 v18, v18, v19
	v_mul_f32_e32 v19, v54, v52
	v_mul_f32_e32 v20, v54, v53
	v_cvt_pk_bf16_f32 v19, v19, v20
	v_mul_f32_e32 v20, v54, v56
	v_mul_f32_e32 v21, v54, v58
	v_cvt_pk_bf16_f32 v20, v20, v21
	v_mul_f32_e32 v21, v54, v60
	v_cvt_pk_bf16_f32 v21, v21, v22
	v_mul_f32_e32 v1, v54, v1
	s_nop 0
	v_mfma_f32_32x32x16_bf16 v[2:17], v[18:21], v[84:87], v[2:17]
	v_mul_f32_e32 v18, v54, v57
	v_mul_f32_e32 v19, v54, v59
	v_cvt_pk_bf16_f32 v18, v18, v19
	v_mul_f32_e32 v19, v54, v79
	v_cvt_pk_bf16_f32 v19, v1, v19
	v_mul_f32_e32 v1, v54, v61
	v_mul_f32_e32 v20, v54, v63
	v_mul_f32_e32 v21, v54, v92
	v_cvt_pk_bf16_f32 v20, v1, v20
	v_mul_f32_e32 v1, v54, v55
	v_cvt_pk_bf16_f32 v21, v1, v21
	s_nop 0
	v_mfma_f32_32x32x16_bf16 v[2:17], v[18:21], v[88:91], v[2:17]
	s_nop 11
	v_cndmask_b32_e64 v146, v193, v2, s[0:1]
	v_cndmask_b32_e64 v145, v3, v193, s[4:5]
	v_cndmask_b32_e64 v144, v193, v4, s[6:7]
	v_cndmask_b32_e64 v143, v193, v5, s[8:9]
	v_cndmask_b32_e64 v142, v193, v6, s[10:11]
	v_cndmask_b32_e64 v141, v193, v7, s[12:13]
	v_cndmask_b32_e64 v140, v193, v8, s[14:15]
	v_cndmask_b32_e64 v139, v193, v9, s[16:17]
	v_cndmask_b32_e64 v138, v193, v10, s[18:19]
	v_cndmask_b32_e64 v137, v193, v11, s[20:21]
	v_cndmask_b32_e64 v136, v193, v12, s[22:23]
	v_cndmask_b32_e64 v135, v193, v13, s[24:25]
	v_cndmask_b32_e64 v134, v193, v14, s[26:27]
	v_cndmask_b32_e64 v133, v193, v15, s[28:29]
	v_cndmask_b32_e64 v119, v193, v16, s[30:31]
	v_cndmask_b32_e64 v117, v193, v17, s[34:35]
; __device__ __forceinline__ float bflo(unsigned w) { return __uint_as_float(w << 16); }
; __device__ __forceinline__ float bfhi(unsigned w) { return __uint_as_float(w & 0xffff0000u); }
; __device__ __forceinline__ void swa_mfma(const Params& P, int li, const bf16_t* __restrict__ proj, bf16_t* __restrict__ mix, LAS unsigned char* ldsl) {
;     ...
;         for (int j = 0; j < 5; ++j) {
;             const int kb = t0 - 128 + 32 * j;
;             tile_to_lds(kimg, stg, lane);
;             if (j < 4) { const int kn1 = kb + 32; tile_load(stg, kbase + (size_t)(kn1 < 0 ? 0 : kn1) * 1280, 1280, lane); }
;             else { const int kb0 = t0 - 128; tile_load(stg, kbase + 128 + (size_t)(kb0 < 0 ? 0 : kb0) * 1280, 1280, lane); }
; #pragma unroll
;             for (int r = 0; r < 16; ++r) s[j][r] = NEG;
;             if (kb >= 0) {
;                 u32x4 kw[4]; frag_read(kw, kimg, r32, hi);
;                 float kss = 0.f;
; #pragma unroll
;                 for (int d0 = 0; d0 < 4; ++d0) {
;                     const float a0 = bflo(kw[d0].x), a1 = bfhi(kw[d0].x), a2 = bflo(kw[d0].y), a3 = bfhi(kw[d0].y), a4 = bflo(kw[d0].z), a5 = bfhi(kw[d0].z), a6 = bflo(kw[d0].w), a7 = bfhi(kw[d0].w);
;                     kss += (a0 * a0 + a1 * a1) + (a2 * a2 + a3 * a3) + (a4 * a4 + a5 * a5) + (a6 * a6 + a7 * a7); }
;                 kss = half_sum(kss);
;                 const float ksc = __builtin_amdgcn_rsqf(kss * (1.f / 64.f) + EPS);
;                 f32x16 acc;
; #pragma unroll
;                 for (int r = 0; r < 16; ++r) acc[r] = 0.f;
; #pragma unroll
;                 for (int d0 = 0; d0 < 4; ++d0) { u32x4 w;
;                     w.x = pk2(bflo(kw[d0].x) * ksc, bfhi(kw[d0].x) * ksc); w.y = pk2(bflo(kw[d0].y) * ksc, bfhi(kw[d0].y) * ksc);
;                     w.z = pk2(bflo(kw[d0].z) * ksc, bfhi(kw[d0].z) * ksc); w.w = pk2(bflo(kw[d0].w) * ksc, bfhi(kw[d0].w) * ksc);
;                     acc = __builtin_amdgcn_mfma_f32_32x32x16_bf16(as_bf(w), as_bf(qf[d0]), acc, 0, 0, 0); }
; #pragma unroll
;                 for (int r = 0; r < 16; ++r) {
;                     bool valid = true;
;                     if (j == 0) valid = crow(r, hi) > r32;
;                     if (j == 4) valid = crow(r, hi) <= r32;
;                     s[j][r] = valid ? acc[r] : NEG;
;                 }
;             }
.LBB0_216:
	v_sub_u32_e64 v1, s48, 64 clamp
	s_movk_i32 s46, 0xa00
	v_mul_lo_u32 v148, v1, s46
	v_lshl_add_u64 v[122:123], v[76:77], 0, v[148:149]
	v_add_co_u32_e32 v2, vcc, s49, v122
	s_cmpk_gt_u32 s48, 0x5f
	s_nop 0
	v_addc_co_u32_e32 v3, vcc, 0, v123, vcc
	global_load_dwordx4 v[16:19], v[122:123], off offset:1024
	global_load_dwordx4 v[20:23], v[2:3], off offset:1024
	v_add_co_u32_e32 v2, vcc, 0xa000, v122
	s_cselect_b64 s[40:41], -1, 0
	s_nop 0
	v_addc_co_u32_e32 v3, vcc, 0, v123, vcc
	v_add_co_u32_e32 v4, vcc, 0xf000, v122
	s_cmpk_lt_u32 s48, 0x60
	s_nop 0
	v_addc_co_u32_e32 v5, vcc, 0, v123, vcc
	global_load_dwordx4 v[36:39], v[2:3], off offset:1024
	global_load_dwordx4 v[44:47], v[4:5], off offset:1024
	v_mov_b32_e32 v1, 0xff800000
	v_mov_b32_e32 v2, 0xff800000
	v_mov_b32_e32 v3, 0xff800000
	v_mov_b32_e32 v4, 0xff800000
	v_mov_b32_e32 v5, 0xff800000
	v_mov_b32_e32 v6, 0xff800000
	v_mov_b32_e32 v7, 0xff800000
	v_mov_b32_e32 v8, 0xff800000
	v_mov_b32_e32 v9, 0xff800000
	v_mov_b32_e32 v10, 0xff800000
	v_mov_b32_e32 v11, 0xff800000
	v_mov_b32_e32 v12, 0xff800000
	v_mov_b32_e32 v13, 0xff800000
	v_mov_b32_e32 v14, 0xff800000
	v_mov_b32_e32 v15, 0xff800000
	s_waitcnt vmcnt(7)
	ds_write_b128 v128, v[24:27]
	s_waitcnt vmcnt(6)
	ds_write_b128 v128, v[28:31] offset:1152
	s_waitcnt vmcnt(5)
	ds_write_b128 v128, v[32:35] offset:2304
	s_waitcnt vmcnt(4)
	ds_write_b128 v128, v[40:43] offset:3456
	s_cbranch_scc1 .LBB0_218
	ds_read_b128 v[0:3], v129
	ds_read_b128 v[4:7], v129 offset:32
	ds_read_b128 v[8:11], v129 offset:64
	ds_read_b128 v[12:15], v129 offset:96
	s_waitcnt lgkmcnt(3)
	v_and_b32_e32 v25, 0xffff0000, v1
	s_waitcnt lgkmcnt(2)
	v_lshlrev_b32_e32 v41, 16, v7
	s_waitcnt lgkmcnt(1)
	v_and_b32_e32 v49, 0xffff0000, v8
	v_and_b32_e32 v51, 0xffff0000, v9
	v_lshlrev_b32_e32 v40, 16, v6
	v_and_b32_e32 v43, 0xffff0000, v7
	v_and_b32_e32 v42, 0xffff0000, v6
	v_lshlrev_b32_e32 v48, 16, v8
	v_lshlrev_b32_e32 v50, 16, v9
	s_waitcnt lgkmcnt(0)
	v_lshlrev_b32_e32 v62, 16, v13
	v_and_b32_e32 v63, 0xffff0000, v13
	v_lshlrev_b32_e32 v54, 16, v10
	v_and_b32_e32 v56, 0xffff0000, v10
	v_pk_mov_b32 v[6:7], v[10:11], v[14:15] op_sel:[1,0]
	v_mul_f32_e32 v8, v49, v49
	v_mul_f32_e32 v10, v51, v51
	v_and_b32_e32 v31, 0xffff0000, v0
	v_and_b32_e32 v30, 0xffff0000, v2
	v_mul_f32_e32 v13, v62, v62
	v_mul_f32_e32 v52, v63, v63
	v_and_b32_e32 v57, 0xffff0000, v12
	v_lshlrev_b32_e32 v58, 16, v11
	v_pk_fma_f32 v[8:9], v[48:49], v[48:49], v[8:9] op_sel_hi:[1,1,0]
	v_pk_fma_f32 v[10:11], v[50:51], v[50:51], v[10:11] op_sel_hi:[1,1,0]
	v_lshlrev_b32_e32 v24, 16, v1
	v_mul_f32_e32 v26, v25, v25
	v_lshlrev_b32_e32 v29, 16, v0
	v_lshlrev_b32_e32 v28, 16, v2
	v_mul_f32_e32 v0, v30, v30
	v_mul_f32_e32 v1, v31, v31
	v_lshlrev_b32_e32 v55, 16, v12
	v_and_b32_e32 v61, 0xffff0000, v7
	v_and_b32_e32 v60, 0xffff0000, v6
	v_mul_f32_e32 v6, v56, v56
	v_mul_f32_e32 v7, v57, v57
	v_mov_b32_e32 v9, v13
	v_mov_b32_e32 v11, v52
	v_pk_fma_f32 v[26:27], v[24:25], v[24:25], v[26:27] op_sel_hi:[1,1,0]
	v_pk_fma_f32 v[0:1], v[28:29], v[28:29], v[0:1]
	v_pk_fma_f32 v[6:7], v[54:55], v[54:55], v[6:7]
	v_pk_add_f32 v[8:9], v[8:9], v[10:11]
	v_pk_add_f32 v[26:27], v[0:1], v[26:27] op_sel:[1,0] op_sel_hi:[0,1]
	v_and_b32_e32 v35, 0xffff0000, v5
	v_and_b32_e32 v34, 0xffff0000, v4
	v_lshlrev_b32_e32 v59, 16, v14
	v_pk_add_f32 v[6:7], v[6:7], v[8:9]
	v_mul_f32_e32 v8, v60, v60
	v_mul_f32_e32 v9, v61, v61
	v_pk_add_f32 v[0:1], v[0:1], v[26:27]
	v_lshlrev_b32_e32 v26, 16, v3
	v_and_b32_e32 v27, 0xffff0000, v3
	v_lshlrev_b32_e32 v33, 16, v5
	v_lshlrev_b32_e32 v32, 16, v4
	v_mul_f32_e32 v2, v34, v34
	v_mul_f32_e32 v3, v35, v35
	v_pk_fma_f32 v[8:9], v[58:59], v[58:59], v[8:9]
	v_pk_fma_f32 v[2:3], v[32:33], v[32:33], v[2:3]
	v_mul_f32_e32 v4, v42, v42
	v_mul_f32_e32 v5, v43, v43
	v_pk_add_f32 v[6:7], v[8:9], v[6:7]
	v_mul_f32_e32 v8, v27, v27
	v_pk_add_f32 v[2:3], v[2:3], v[2:3] op_sel:[0,1] op_sel_hi:[1,0]
	v_pk_fma_f32 v[4:5], v[40:41], v[40:41], v[4:5]
	v_lshlrev_b32_e32 v53, 16, v15
	v_pk_fma_f32 v[8:9], v[26:27], v[26:27], v[8:9] op_sel_hi:[1,1,0]
	v_pk_add_f32 v[2:3], v[4:5], v[2:3]
	v_and_b32_e32 v79, 0xffff0000, v15
	v_mov_b32_e32 v52, v8
	v_mov_b32_e32 v10, v0
	v_mov_b32_e32 v11, v53
	v_mul_f32_e32 v92, v79, v79
	v_pk_add_f32 v[0:1], v[8:9], v[0:1]
	v_mul_f32_e32 v8, v52, v10
	v_mul_f32_e32 v9, v53, v11
	v_pk_add_f32 v[2:3], v[4:5], v[2:3] op_sel:[1,0] op_sel_hi:[0,1]
	v_mov_b32_e32 v1, v9
	v_mov_b32_e32 v3, v92
	v_pk_add_f32 v[0:1], v[0:1], v[2:3]
	s_nop 0
	v_pk_add_f32 v[0:1], v[0:1], v[6:7]
	s_nop 0
	v_pk_add_f32 v[0:1], v[0:1], v[0:1] op_sel:[0,1] op_sel_hi:[1,0]
	s_nop 0
	v_mov_b32_e32 v1, v0
	s_nop 1
	v_permlane32_swap_b32_e32 v0, v1
	v_add_f32_e32 v0, v0, v1
	v_fmamk_f32 v0, v0, 0x3c800000, v185
	v_rsq_f32_e32 v52, v0
	s_nop 0
	v_mul_f32_e32 v0, v52, v29
	v_mul_f32_e32 v1, v52, v31
	v_cvt_pk_bf16_f32 v0, v0, v1
	v_mul_f32_e32 v1, v52, v24
	v_mul_f32_e32 v2, v52, v25
	v_cvt_pk_bf16_f32 v1, v1, v2
	v_mul_f32_e32 v2, v52, v28
	v_mul_f32_e32 v3, v52, v30
	v_cvt_pk_bf16_f32 v2, v2, v3
	v_mul_f32_e32 v3, v52, v26
	v_mul_f32_e32 v4, v52, v27
	v_cvt_pk_bf16_f32 v3, v3, v4
	v_mul_f32_e32 v24, v52, v32
	v_mfma_f32_32x32x16_bf16 v[0:15], v[0:3], v[64:67], 0
	v_mul_f32_e32 v25, v52, v34
	v_cvt_pk_bf16_f32 v24, v24, v25
	v_mul_f32_e32 v25, v52, v33
	v_mul_f32_e32 v26, v52, v35
	v_cvt_pk_bf16_f32 v25, v25, v26
	v_mul_f32_e32 v26, v52, v40
	v_mul_f32_e32 v27, v52, v42
	v_cvt_pk_bf16_f32 v26, v26, v27
	v_mul_f32_e32 v27, v52, v41
	v_mul_f32_e32 v28, v52, v43
	v_cvt_pk_bf16_f32 v27, v27, v28
	v_mul_f32_e32 v28, v52, v60
	v_mfma_f32_32x32x16_bf16 v[0:15], v[24:27], v[80:83], v[0:15]
	v_mul_f32_e32 v24, v52, v48
	v_mul_f32_e32 v25, v52, v49
	v_cvt_pk_bf16_f32 v24, v24, v25
	v_mul_f32_e32 v25, v52, v50
	v_mul_f32_e32 v26, v52, v51
	v_cvt_pk_bf16_f32 v25, v25, v26
	v_mul_f32_e32 v26, v52, v54
	v_mul_f32_e32 v27, v52, v56
	v_cvt_pk_bf16_f32 v26, v26, v27
	v_mul_f32_e32 v27, v52, v58
	v_cvt_pk_bf16_f32 v27, v27, v28
	v_mul_f32_e32 v28, v52, v79
	s_nop 0
	v_mfma_f32_32x32x16_bf16 v[0:15], v[24:27], v[84:87], v[0:15]
	v_mul_f32_e32 v24, v52, v55
	v_mul_f32_e32 v25, v52, v57
	v_cvt_pk_bf16_f32 v24, v24, v25
	v_mul_f32_e32 v25, v52, v62
	v_mul_f32_e32 v26, v52, v63
	v_cvt_pk_bf16_f32 v25, v25, v26
	v_mul_f32_e32 v26, v52, v59
	v_mul_f32_e32 v27, v52, v61
	v_cvt_pk_bf16_f32 v26, v26, v27
	v_mul_f32_e32 v27, v52, v53
	v_cvt_pk_bf16_f32 v27, v27, v28
	s_nop 1
	v_mfma_f32_32x32x16_bf16 v[0:15], v[24:27], v[88:91], v[0:15]
; __device__ __forceinline__ float bflo(unsigned w) { return __uint_as_float(w << 16); }
; __device__ __forceinline__ float bfhi(unsigned w) { return __uint_as_float(w & 0xffff0000u); }
; __device__ __forceinline__ void swa_mfma(const Params& P, int li, const bf16_t* __restrict__ proj, bf16_t* __restrict__ mix, LAS unsigned char* ldsl) {
;     ...
;         for (int j = 0; j < 5; ++j) {
;             const int kb = t0 - 128 + 32 * j;
;             tile_to_lds(kimg, stg, lane);
;             if (j < 4) { const int kn1 = kb + 32; tile_load(stg, kbase + (size_t)(kn1 < 0 ? 0 : kn1) * 1280, 1280, lane); }
;             else { const int kb0 = t0 - 128; tile_load(stg, kbase + 128 + (size_t)(kb0 < 0 ? 0 : kb0) * 1280, 1280, lane); }
; #pragma unroll
;             for (int r = 0; r < 16; ++r) s[j][r] = NEG;
;             if (kb >= 0) {
;                 u32x4 kw[4]; frag_read(kw, kimg, r32, hi);
;                 float kss = 0.f;
; #pragma unroll
;                 for (int d0 = 0; d0 < 4; ++d0) {
;                     const float a0 = bflo(kw[d0].x), a1 = bfhi(kw[d0].x), a2 = bflo(kw[d0].y), a3 = bfhi(kw[d0].y), a4 = bflo(kw[d0].z), a5 = bfhi(kw[d0].z), a6 = bflo(kw[d0].w), a7 = bfhi(kw[d0].w);
;                     kss += (a0 * a0 + a1 * a1) + (a2 * a2 + a3 * a3) + (a4 * a4 + a5 * a5) + (a6 * a6 + a7 * a7); }
;                 kss = half_sum(kss);
;                 const float ksc = __builtin_amdgcn_rsqf(kss * (1.f / 64.f) + EPS);
;                 f32x16 acc;
; #pragma unroll
;                 for (int r = 0; r < 16; ++r) acc[r] = 0.f;
; #pragma unroll
;                 for (int d0 = 0; d0 < 4; ++d0) { u32x4 w;
;                     w.x = pk2(bflo(kw[d0].x) * ksc, bfhi(kw[d0].x) * ksc); w.y = pk2(bflo(kw[d0].y) * ksc, bfhi(kw[d0].y) * ksc);
;                     w.z = pk2(bflo(kw[d0].z) * ksc, bfhi(kw[d0].z) * ksc); w.w = pk2(bflo(kw[d0].w) * ksc, bfhi(kw[d0].w) * ksc);
;                     acc = __builtin_amdgcn_mfma_f32_32x32x16_bf16(as_bf(w), as_bf(qf[d0]), acc, 0, 0, 0); }
; #pragma unroll
;                 for (int r = 0; r < 16; ++r) {
;                     bool valid = true;
;                     if (j == 0) valid = crow(r, hi) > r32;
;                     if (j == 4) valid = crow(r, hi) <= r32;
;                     s[j][r] = valid ? acc[r] : NEG;
;                 }
;             }
.LBB0_218:
	v_sub_u32_e64 v24, s48, 32 clamp
	v_mul_lo_u32 v148, v24, s46
	v_lshl_add_u64 v[124:125], v[76:77], 0, v[148:149]
	v_add_co_u32_e32 v24, vcc, s49, v124
	s_cmp_gt_u32 s48, 63
	s_nop 0
	v_addc_co_u32_e32 v25, vcc, 0, v125, vcc
	global_load_dwordx4 v[48:51], v[124:125], off offset:1024
	global_load_dwordx4 v[52:55], v[24:25], off offset:1024
	v_add_co_u32_e32 v24, vcc, 0xa000, v124
	v_mov_b32_e32 v32, 0xff800000
	s_nop 0
	v_addc_co_u32_e32 v25, vcc, 0, v125, vcc
	v_add_co_u32_e32 v26, vcc, 0xf000, v124
	s_cselect_b64 s[46:47], -1, 0
	s_nop 0
	v_addc_co_u32_e32 v27, vcc, 0, v125, vcc
	global_load_dwordx4 v[56:59], v[24:25], off offset:1024
	global_load_dwordx4 v[60:63], v[26:27], off offset:1024
	s_waitcnt vmcnt(7)
	ds_write_b128 v128, v[16:19]
	s_waitcnt vmcnt(6)
	ds_write_b128 v128, v[20:23] offset:1152
	s_waitcnt vmcnt(5)
	ds_write_b128 v128, v[36:39] offset:2304
	s_waitcnt vmcnt(4)
	ds_write_b128 v128, v[44:47] offset:3456
	s_cmp_lt_u32 s48, 64
	v_mov_b32_e32 v33, 0xff800000
	v_mov_b32_e32 v34, 0xff800000
	v_mov_b32_e32 v35, 0xff800000
	v_mov_b32_e32 v36, 0xff800000
	v_mov_b32_e32 v37, 0xff800000
	v_mov_b32_e32 v38, 0xff800000
	v_mov_b32_e32 v39, 0xff800000
	v_mov_b32_e32 v40, 0xff800000
	v_mov_b32_e32 v41, 0xff800000
	v_mov_b32_e32 v42, 0xff800000
	v_mov_b32_e32 v43, 0xff800000
	v_mov_b32_e32 v44, 0xff800000
	v_mov_b32_e32 v45, 0xff800000
	v_mov_b32_e32 v46, 0xff800000
	v_mov_b32_e32 v47, 0xff800000
	s_mov_b32 s68, s50
	s_cbranch_scc1 .LBB0_220
	ds_read_b128 v[16:19], v129
	ds_read_b128 v[20:23], v129 offset:32
	ds_read_b128 v[24:27], v129 offset:64
	ds_read_b128 v[28:31], v129 offset:96
	s_waitcnt lgkmcnt(3)
	v_and_b32_e32 v33, 0xffff0000, v17
	v_and_b32_e32 v39, 0xffff0000, v16
	s_waitcnt lgkmcnt(1)
	v_and_b32_e32 v97, 0xffff0000, v24
	v_lshlrev_b32_e32 v96, 16, v24
	v_lshlrev_b32_e32 v24, 16, v25
	v_and_b32_e32 v25, 0xffff0000, v25
	s_waitcnt lgkmcnt(0)
	v_lshlrev_b32_e32 v79, 16, v29
	v_and_b32_e32 v102, 0xffff0000, v29
	v_lshlrev_b32_e32 v29, 16, v31
	v_lshlrev_b32_e32 v99, 16, v28
	v_and_b32_e32 v101, 0xffff0000, v28
	v_mul_f32_e32 v28, v97, v97
	v_and_b32_e32 v38, 0xffff0000, v18
	v_mul_f32_e32 v46, v79, v79
	v_pk_fma_f32 v[44:45], v[96:97], v[96:97], v[28:29] op_sel_hi:[1,1,0]
	v_mul_f32_e32 v28, v25, v25
	v_lshlrev_b32_e32 v32, 16, v17
	v_mul_f32_e32 v34, v33, v33
	v_lshlrev_b32_e32 v37, 16, v16
	v_lshlrev_b32_e32 v36, 16, v18
	v_mul_f32_e32 v16, v38, v38
	v_mul_f32_e32 v17, v39, v39
	v_mul_f32_e32 v104, v102, v102
	v_and_b32_e32 v100, 0xffff0000, v26
	v_pk_mov_b32 v[42:43], v[26:27], v[30:31] op_sel:[1,0]
	v_mov_b32_e32 v45, v46
	v_pk_fma_f32 v[46:47], v[24:25], v[24:25], v[28:29] op_sel_hi:[1,1,0]
	v_pk_fma_f32 v[34:35], v[32:33], v[32:33], v[34:35] op_sel_hi:[1,1,0]
	v_pk_fma_f32 v[16:17], v[36:37], v[36:37], v[16:17]
	v_and_b32_e32 v103, 0xffff0000, v31
	v_lshlrev_b32_e32 v98, 16, v26
	v_lshlrev_b32_e32 v31, 16, v30
	v_lshlrev_b32_e32 v30, 16, v27
	v_and_b32_e32 v27, 0xffff0000, v43
	v_and_b32_e32 v26, 0xffff0000, v42
	v_mul_f32_e32 v42, v100, v100
	v_mul_f32_e32 v43, v101, v101
	v_mov_b32_e32 v47, v104
	v_pk_add_f32 v[34:35], v[16:17], v[34:35] op_sel:[1,0] op_sel_hi:[0,1]
	v_lshlrev_b32_e32 v93, 16, v21
	v_lshlrev_b32_e32 v92, 16, v20
	v_and_b32_e32 v21, 0xffff0000, v21
	v_and_b32_e32 v20, 0xffff0000, v20
	v_pk_fma_f32 v[42:43], v[98:99], v[98:99], v[42:43]
	v_pk_add_f32 v[44:45], v[44:45], v[46:47]
	v_pk_add_f32 v[16:17], v[16:17], v[34:35]
	v_lshlrev_b32_e32 v34, 16, v19
	v_and_b32_e32 v35, 0xffff0000, v19
	v_mul_f32_e32 v18, v20, v20
	v_mul_f32_e32 v19, v21, v21
	v_lshlrev_b32_e32 v95, 16, v23
	v_lshlrev_b32_e32 v94, 16, v22
	v_and_b32_e32 v23, 0xffff0000, v23
	v_and_b32_e32 v22, 0xffff0000, v22
	v_pk_add_f32 v[42:43], v[42:43], v[44:45]
	v_mul_f32_e32 v44, v26, v26
	v_mul_f32_e32 v45, v27, v27
	v_pk_fma_f32 v[18:19], v[92:93], v[92:93], v[18:19]
	v_mul_f32_e32 v40, v22, v22
	v_mul_f32_e32 v41, v23, v23
	v_pk_fma_f32 v[44:45], v[30:31], v[30:31], v[44:45]
	v_mul_f32_e32 v28, v35, v35
	v_pk_add_f32 v[18:19], v[18:19], v[18:19] op_sel:[0,1] op_sel_hi:[1,0]
	v_pk_fma_f32 v[40:41], v[94:95], v[94:95], v[40:41]
	v_pk_add_f32 v[42:43], v[44:45], v[42:43]
	v_pk_fma_f32 v[44:45], v[34:35], v[34:35], v[28:29] op_sel_hi:[1,1,0]
	v_pk_add_f32 v[18:19], v[40:41], v[18:19]
	v_mov_b32_e32 v28, v44
	v_mov_b32_e32 v46, v16
	v_mov_b32_e32 v47, v29
	v_mul_f32_e32 v105, v103, v103
	v_pk_add_f32 v[16:17], v[44:45], v[16:17]
	v_mul_f32_e32 v44, v28, v46
	v_mul_f32_e32 v45, v29, v47
	v_pk_add_f32 v[18:19], v[40:41], v[18:19] op_sel:[1,0] op_sel_hi:[0,1]
	v_mov_b32_e32 v17, v45
	v_mov_b32_e32 v19, v105
	v_pk_add_f32 v[16:17], v[16:17], v[18:19]
	s_nop 0
	v_pk_add_f32 v[16:17], v[16:17], v[42:43]
	s_nop 0
	v_pk_add_f32 v[16:17], v[16:17], v[16:17] op_sel:[0,1] op_sel_hi:[1,0]
	s_nop 0
	v_mov_b32_e32 v17, v16
	s_nop 1
	v_permlane32_swap_b32_e32 v16, v17
	v_add_f32_e32 v16, v16, v17
	v_fmamk_f32 v16, v16, 0x3c800000, v185
	v_rsq_f32_e32 v28, v16
	s_nop 0
	v_mul_f32_e32 v16, v28, v37
	v_mul_f32_e32 v17, v28, v39
	v_cvt_pk_bf16_f32 v16, v16, v17
	v_mul_f32_e32 v17, v28, v32
	v_mul_f32_e32 v18, v28, v33
	v_cvt_pk_bf16_f32 v17, v17, v18
	v_mul_f32_e32 v18, v28, v36
	v_mul_f32_e32 v19, v28, v38
	v_cvt_pk_bf16_f32 v18, v18, v19
	v_mul_f32_e32 v19, v28, v34
	v_mul_f32_e32 v32, v28, v35
	v_cvt_pk_bf16_f32 v19, v19, v32
	s_nop 0
	v_mfma_f32_32x32x16_bf16 v[32:47], v[16:19], v[64:67], 0
	v_mul_f32_e32 v16, v28, v92
	v_mul_f32_e32 v17, v28, v20
	v_cvt_pk_bf16_f32 v16, v16, v17
	v_mul_f32_e32 v17, v28, v93
	v_mul_f32_e32 v18, v28, v21
	v_cvt_pk_bf16_f32 v17, v17, v18
	v_mul_f32_e32 v18, v28, v94
	v_mul_f32_e32 v19, v28, v22
	v_cvt_pk_bf16_f32 v18, v18, v19
	v_mul_f32_e32 v19, v28, v95
	v_mul_f32_e32 v20, v28, v23
	v_cvt_pk_bf16_f32 v19, v19, v20
	v_mul_f32_e32 v20, v28, v26
	v_mfma_f32_32x32x16_bf16 v[32:47], v[16:19], v[80:83], v[32:47]
	v_mul_f32_e32 v16, v28, v96
	v_mul_f32_e32 v17, v28, v97
	v_cvt_pk_bf16_f32 v16, v16, v17
	v_mul_f32_e32 v17, v28, v24
	v_mul_f32_e32 v18, v28, v25
	v_cvt_pk_bf16_f32 v17, v17, v18
	v_mul_f32_e32 v18, v28, v98
	v_mul_f32_e32 v19, v28, v100
	v_cvt_pk_bf16_f32 v18, v18, v19
	v_mul_f32_e32 v19, v28, v30
	v_cvt_pk_bf16_f32 v19, v19, v20
	v_mul_f32_e32 v20, v28, v103
	s_nop 0
	v_mfma_f32_32x32x16_bf16 v[32:47], v[16:19], v[84:87], v[32:47]
	v_mul_f32_e32 v16, v28, v99
	v_mul_f32_e32 v17, v28, v101
	v_cvt_pk_bf16_f32 v16, v16, v17
	v_mul_f32_e32 v17, v28, v79
	v_mul_f32_e32 v18, v28, v102
	v_cvt_pk_bf16_f32 v17, v17, v18
	v_mul_f32_e32 v18, v28, v31
	v_mul_f32_e32 v19, v28, v27
	v_cvt_pk_bf16_f32 v18, v18, v19
	v_mul_f32_e32 v19, v28, v29
	v_cvt_pk_bf16_f32 v19, v19, v20
	s_nop 1
	v_mfma_f32_32x32x16_bf16 v[32:47], v[16:19], v[88:91], v[32:47]
; __device__ __forceinline__ float bflo(unsigned w) { return __uint_as_float(w << 16); }
; __device__ __forceinline__ float bfhi(unsigned w) { return __uint_as_float(w & 0xffff0000u); }
; __device__ __forceinline__ void swa_mfma(const Params& P, int li, const bf16_t* __restrict__ proj, bf16_t* __restrict__ mix, LAS unsigned char* ldsl) {
;     ...
;         for (int j = 0; j < 5; ++j) {
;             const int kb = t0 - 128 + 32 * j;
;             tile_to_lds(kimg, stg, lane);
;             if (j < 4) { const int kn1 = kb + 32; tile_load(stg, kbase + (size_t)(kn1 < 0 ? 0 : kn1) * 1280, 1280, lane); }
;             else { const int kb0 = t0 - 128; tile_load(stg, kbase + 128 + (size_t)(kb0 < 0 ? 0 : kb0) * 1280, 1280, lane); }
; #pragma unroll
;             for (int r = 0; r < 16; ++r) s[j][r] = NEG;
;             if (kb >= 0) {
;                 u32x4 kw[4]; frag_read(kw, kimg, r32, hi);
;                 float kss = 0.f;
; #pragma unroll
;                 for (int d0 = 0; d0 < 4; ++d0) {
;                     const float a0 = bflo(kw[d0].x), a1 = bfhi(kw[d0].x), a2 = bflo(kw[d0].y), a3 = bfhi(kw[d0].y), a4 = bflo(kw[d0].z), a5 = bfhi(kw[d0].z), a6 = bflo(kw[d0].w), a7 = bfhi(kw[d0].w);
;                     kss += (a0 * a0 + a1 * a1) + (a2 * a2 + a3 * a3) + (a4 * a4 + a5 * a5) + (a6 * a6 + a7 * a7); }
;                 kss = half_sum(kss);
;                 const float ksc = __builtin_amdgcn_rsqf(kss * (1.f / 64.f) + EPS);
;                 f32x16 acc;
; #pragma unroll
;                 for (int r = 0; r < 16; ++r) acc[r] = 0.f;
; #pragma unroll
;                 for (int d0 = 0; d0 < 4; ++d0) { u32x4 w;
;                     w.x = pk2(bflo(kw[d0].x) * ksc, bfhi(kw[d0].x) * ksc); w.y = pk2(bflo(kw[d0].y) * ksc, bfhi(kw[d0].y) * ksc);
;                     w.z = pk2(bflo(kw[d0].z) * ksc, bfhi(kw[d0].z) * ksc); w.w = pk2(bflo(kw[d0].w) * ksc, bfhi(kw[d0].w) * ksc);
;                     acc = __builtin_amdgcn_mfma_f32_32x32x16_bf16(as_bf(w), as_bf(qf[d0]), acc, 0, 0, 0); }
; #pragma unroll
;                 for (int r = 0; r < 16; ++r) {
;                     bool valid = true;
;                     if (j == 0) valid = crow(r, hi) > r32;
;                     if (j == 4) valid = crow(r, hi) <= r32;
;                     s[j][r] = valid ? acc[r] : NEG;
;                 }
;             }
.LBB0_220:
	s_mov_b32 s61, s57
	s_mul_i32 s60, s48, 0xa00
	v_lshl_add_u64 v[126:127], v[76:77], 0, s[60:61]
	v_add_co_u32_e32 v20, vcc, s49, v126
	s_cmp_lg_u32 s48, 0
	s_nop 0
	v_addc_co_u32_e32 v21, vcc, 0, v127, vcc
	v_add_co_u32_e32 v24, vcc, 0xa000, v126
	global_load_dwordx4 v[16:19], v[126:127], off offset:1024
	s_nop 0
	global_load_dwordx4 v[20:23], v[20:21], off offset:1024
	v_addc_co_u32_e32 v25, vcc, 0, v127, vcc
	v_add_co_u32_e32 v28, vcc, 0xf000, v126
	s_cselect_b64 s[48:49], -1, 0
	s_nop 0
	v_addc_co_u32_e32 v29, vcc, 0, v127, vcc
	global_load_dwordx4 v[24:27], v[24:25], off offset:1024
	s_nop 0
	global_load_dwordx4 v[28:31], v[28:29], off offset:1024
	s_mov_b32 s73, s57
	s_and_b64 vcc, exec, s[48:49]
	s_waitcnt vmcnt(7)
	ds_write_b128 v128, v[48:51]
	s_waitcnt vmcnt(6)
	ds_write_b128 v128, v[52:55] offset:1152
	s_waitcnt vmcnt(5)
	ds_write_b128 v128, v[56:59] offset:2304
	s_waitcnt vmcnt(4)
	ds_write_b128 v128, v[60:63] offset:3456
	s_cbranch_vccz .LBB0_231
	ds_read_b128 v[48:51], v129
	ds_read_b128 v[52:55], v129 offset:32
	ds_read_b128 v[56:59], v129 offset:64
	ds_read_b128 v[60:63], v129 offset:96
	s_waitcnt lgkmcnt(3)
	v_and_b32_e32 v77, 0xffff0000, v49
	s_waitcnt lgkmcnt(2)
	v_lshlrev_b32_e32 v103, 16, v55
	s_waitcnt lgkmcnt(1)
	v_and_b32_e32 v107, 0xffff0000, v56
	v_and_b32_e32 v153, 0xffff0000, v57
	v_lshlrev_b32_e32 v102, 16, v54
	v_and_b32_e32 v105, 0xffff0000, v55
	v_and_b32_e32 v104, 0xffff0000, v54
	v_lshlrev_b32_e32 v106, 16, v56
	v_lshlrev_b32_e32 v152, 16, v57
	s_waitcnt lgkmcnt(0)
	v_lshlrev_b32_e32 v79, 16, v61
	v_and_b32_e32 v147, 0xffff0000, v61
	v_lshlrev_b32_e32 v156, 16, v58
	v_and_b32_e32 v158, 0xffff0000, v58
	v_pk_mov_b32 v[54:55], v[58:59], v[62:63] op_sel:[1,0]
	v_mul_f32_e32 v56, v107, v107
	v_mul_f32_e32 v58, v153, v153
	v_and_b32_e32 v97, 0xffff0000, v48
	v_and_b32_e32 v96, 0xffff0000, v50
	v_mul_f32_e32 v61, v79, v79
	v_mul_f32_e32 v151, v147, v147
	v_and_b32_e32 v159, 0xffff0000, v60
	v_lshlrev_b32_e32 v160, 16, v59
	v_pk_fma_f32 v[56:57], v[106:107], v[106:107], v[56:57] op_sel_hi:[1,1,0]
	v_pk_fma_f32 v[58:59], v[152:153], v[152:153], v[58:59] op_sel_hi:[1,1,0]
	v_lshlrev_b32_e32 v76, 16, v49
	v_mul_f32_e32 v92, v77, v77
	v_lshlrev_b32_e32 v95, 16, v48
	v_lshlrev_b32_e32 v94, 16, v50
	v_mul_f32_e32 v48, v96, v96
	v_mul_f32_e32 v49, v97, v97
	v_lshlrev_b32_e32 v157, 16, v60
	v_and_b32_e32 v163, 0xffff0000, v55
	v_and_b32_e32 v162, 0xffff0000, v54
	v_mul_f32_e32 v54, v158, v158
	v_mul_f32_e32 v55, v159, v159
	v_mov_b32_e32 v57, v61
	v_mov_b32_e32 v59, v151
	v_pk_fma_f32 v[92:93], v[76:77], v[76:77], v[92:93] op_sel_hi:[1,1,0]
	v_pk_fma_f32 v[48:49], v[94:95], v[94:95], v[48:49]
	v_pk_fma_f32 v[54:55], v[156:157], v[156:157], v[54:55]
	v_pk_add_f32 v[56:57], v[56:57], v[58:59]
	v_pk_add_f32 v[92:93], v[48:49], v[92:93] op_sel:[1,0] op_sel_hi:[0,1]
	v_and_b32_e32 v101, 0xffff0000, v53
	v_and_b32_e32 v100, 0xffff0000, v52
	v_lshlrev_b32_e32 v161, 16, v62
	v_pk_add_f32 v[54:55], v[54:55], v[56:57]
	v_mul_f32_e32 v56, v162, v162
	v_mul_f32_e32 v57, v163, v163
	v_pk_add_f32 v[48:49], v[48:49], v[92:93]
	v_lshlrev_b32_e32 v92, 16, v51
	v_and_b32_e32 v93, 0xffff0000, v51
	v_lshlrev_b32_e32 v99, 16, v53
	v_lshlrev_b32_e32 v98, 16, v52
	v_mul_f32_e32 v50, v100, v100
	v_mul_f32_e32 v51, v101, v101
	v_pk_fma_f32 v[56:57], v[160:161], v[160:161], v[56:57]
	v_pk_fma_f32 v[50:51], v[98:99], v[98:99], v[50:51]
	v_mul_f32_e32 v52, v104, v104
	v_mul_f32_e32 v53, v105, v105
	v_pk_add_f32 v[54:55], v[56:57], v[54:55]
	v_mul_f32_e32 v56, v93, v93
	v_pk_add_f32 v[50:51], v[50:51], v[50:51] op_sel:[0,1] op_sel_hi:[1,0]
	v_pk_fma_f32 v[52:53], v[102:103], v[102:103], v[52:53]
	v_lshlrev_b32_e32 v155, 16, v63
	v_pk_fma_f32 v[56:57], v[92:93], v[92:93], v[56:57] op_sel_hi:[1,1,0]
	v_pk_add_f32 v[50:51], v[52:53], v[50:51]
	v_and_b32_e32 v148, 0xffff0000, v63
	v_mov_b32_e32 v154, v56
	v_mov_b32_e32 v58, v48
	v_mov_b32_e32 v59, v155
	v_mul_f32_e32 v164, v148, v148
	v_pk_add_f32 v[48:49], v[56:57], v[48:49]
	v_mul_f32_e32 v56, v154, v58
	v_mul_f32_e32 v57, v155, v59
	v_pk_add_f32 v[50:51], v[52:53], v[50:51] op_sel:[1,0] op_sel_hi:[0,1]
	v_mov_b32_e32 v49, v57
	v_mov_b32_e32 v51, v164
	v_pk_add_f32 v[48:49], v[48:49], v[50:51]
	s_nop 0
	v_pk_add_f32 v[48:49], v[48:49], v[54:55]
	s_nop 0
	v_pk_add_f32 v[48:49], v[48:49], v[48:49] op_sel:[0,1] op_sel_hi:[1,0]
	s_nop 0
	v_mov_b32_e32 v49, v48
	s_nop 1
	v_permlane32_swap_b32_e32 v48, v49
	v_add_f32_e32 v48, v48, v49
	v_fmamk_f32 v48, v48, 0x3c800000, v185
	v_rsq_f32_e32 v151, v48
	s_nop 0
	v_mul_f32_e32 v48, v151, v95
	v_mul_f32_e32 v49, v151, v97
	v_cvt_pk_bf16_f32 v48, v48, v49
	v_mul_f32_e32 v49, v151, v76
	v_mul_f32_e32 v50, v151, v77
	v_cvt_pk_bf16_f32 v49, v49, v50
	v_mul_f32_e32 v50, v151, v94
	v_mul_f32_e32 v51, v151, v96
	v_cvt_pk_bf16_f32 v50, v50, v51
	v_mul_f32_e32 v51, v151, v92
	v_mul_f32_e32 v52, v151, v93
	v_cvt_pk_bf16_f32 v51, v51, v52
	v_mul_f32_e32 v76, v151, v98
	v_mfma_f32_32x32x16_bf16 v[48:63], v[48:51], v[64:67], 0
	v_mul_f32_e32 v77, v151, v100
	v_cvt_pk_bf16_f32 v92, v76, v77
	v_mul_f32_e32 v76, v151, v99
	v_mul_f32_e32 v77, v151, v101
	v_cvt_pk_bf16_f32 v93, v76, v77
	v_mul_f32_e32 v76, v151, v102
	v_mul_f32_e32 v77, v151, v104
	v_cvt_pk_bf16_f32 v94, v76, v77
	v_mul_f32_e32 v76, v151, v103
	v_mul_f32_e32 v77, v151, v105
	v_cvt_pk_bf16_f32 v95, v76, v77
	v_mul_f32_e32 v76, v151, v106
	v_mfma_f32_32x32x16_bf16 v[48:63], v[92:95], v[80:83], v[48:63]
	v_mul_f32_e32 v77, v151, v107
	v_cvt_pk_bf16_f32 v92, v76, v77
	v_mul_f32_e32 v76, v151, v152
	v_mul_f32_e32 v77, v151, v153
	v_cvt_pk_bf16_f32 v93, v76, v77
	v_mul_f32_e32 v76, v151, v156
	v_mul_f32_e32 v77, v151, v158
	v_cvt_pk_bf16_f32 v94, v76, v77
	v_mul_f32_e32 v76, v151, v160
	v_mul_f32_e32 v77, v151, v162
	v_cvt_pk_bf16_f32 v95, v76, v77
	v_mul_f32_e32 v76, v151, v157
	v_mfma_f32_32x32x16_bf16 v[48:63], v[92:95], v[84:87], v[48:63]
	v_mul_f32_e32 v77, v151, v159
	v_cvt_pk_bf16_f32 v92, v76, v77
	v_mul_f32_e32 v76, v151, v79
	v_mul_f32_e32 v77, v151, v147
	v_cvt_pk_bf16_f32 v93, v76, v77
	v_mul_f32_e32 v76, v151, v161
	v_mul_f32_e32 v77, v151, v163
	v_cvt_pk_bf16_f32 v94, v76, v77
	v_mul_f32_e32 v76, v151, v155
	v_mul_f32_e32 v77, v151, v148
	v_cvt_pk_bf16_f32 v95, v76, v77
	s_nop 0
	v_mfma_f32_32x32x16_bf16 v[48:63], v[92:95], v[88:91], v[48:63]
	s_cbranch_execnz .LBB0_223

; __device__ __forceinline__ float bflo(unsigned w) { return __uint_as_float(w << 16); }
; __device__ __forceinline__ float bfhi(unsigned w) { return __uint_as_float(w & 0xffff0000u); }
; __device__ __forceinline__ void swa_mfma(const Params& P, int li, const bf16_t* __restrict__ proj, bf16_t* __restrict__ mix, LAS unsigned char* ldsl) {
;     ...
;         for (int j = 0; j < 5; ++j) {
;             const int kb = t0 - 128 + 32 * j;
;             tile_to_lds(kimg, stg, lane);
;             if (j < 4) { const int kn1 = kb + 32; tile_load(stg, kbase + (size_t)(kn1 < 0 ? 0 : kn1) * 1280, 1280, lane); }
;             else { const int kb0 = t0 - 128; tile_load(stg, kbase + 128 + (size_t)(kb0 < 0 ? 0 : kb0) * 1280, 1280, lane); }
; #pragma unroll
;             for (int r = 0; r < 16; ++r) s[j][r] = NEG;
;             if (kb >= 0) {
;                 u32x4 kw[4]; frag_read(kw, kimg, r32, hi);
;                 float kss = 0.f;
; #pragma unroll
;                 for (int d0 = 0; d0 < 4; ++d0) {
;                     const float a0 = bflo(kw[d0].x), a1 = bfhi(kw[d0].x), a2 = bflo(kw[d0].y), a3 = bfhi(kw[d0].y), a4 = bflo(kw[d0].z), a5 = bfhi(kw[d0].z), a6 = bflo(kw[d0].w), a7 = bfhi(kw[d0].w);
;                     kss += (a0 * a0 + a1 * a1) + (a2 * a2 + a3 * a3) + (a4 * a4 + a5 * a5) + (a6 * a6 + a7 * a7); }
;                 kss = half_sum(kss);
;                 const float ksc = __builtin_amdgcn_rsqf(kss * (1.f / 64.f) + EPS);
;                 f32x16 acc;
; #pragma unroll
;                 for (int r = 0; r < 16; ++r) acc[r] = 0.f;
; #pragma unroll
;                 for (int d0 = 0; d0 < 4; ++d0) { u32x4 w;
;                     w.x = pk2(bflo(kw[d0].x) * ksc, bfhi(kw[d0].x) * ksc); w.y = pk2(bflo(kw[d0].y) * ksc, bfhi(kw[d0].y) * ksc);
;                     w.z = pk2(bflo(kw[d0].z) * ksc, bfhi(kw[d0].z) * ksc); w.w = pk2(bflo(kw[d0].w) * ksc, bfhi(kw[d0].w) * ksc);
;                     acc = __builtin_amdgcn_mfma_f32_32x32x16_bf16(as_bf(w), as_bf(qf[d0]), acc, 0, 0, 0); }
; #pragma unroll
;                 for (int r = 0; r < 16; ++r) {
;                     bool valid = true;
;                     if (j == 0) valid = crow(r, hi) > r32;
;                     if (j == 4) valid = crow(r, hi) <= r32;
;                     s[j][r] = valid ? acc[r] : NEG;
;                 }
;             }
.LBB0_223:
	s_waitcnt vmcnt(3)
	ds_write_b128 v128, v[16:19]
	s_waitcnt vmcnt(2)
	ds_write_b128 v128, v[20:23] offset:1152
	s_waitcnt vmcnt(1)
	ds_write_b128 v128, v[24:27] offset:2304
	s_waitcnt vmcnt(0)
	ds_write_b128 v128, v[28:31] offset:3456
	ds_read_b128 v[16:19], v129
	global_load_dwordx4 v[92:95], v[74:75], off offset:1280
	ds_read_b128 v[20:23], v129 offset:32
	ds_read_b128 v[24:27], v129 offset:64
	ds_read_b128 v[28:31], v129 offset:96
	v_mul_f32_e32 v147, 0x3fb8aa3b, v78
	s_mov_b32 s72, s73
	s_waitcnt lgkmcnt(3)
	v_lshlrev_b32_e32 v74, 16, v17
	v_and_b32_e32 v75, 0xffff0000, v17
	v_lshlrev_b32_e32 v79, 16, v16
	v_and_b32_e32 v17, 0xffff0000, v16
	v_and_b32_e32 v16, 0xffff0000, v18
	v_mul_f32_e32 v76, v75, v75
	v_lshlrev_b32_e32 v78, 16, v18
	v_mul_f32_e32 v96, v16, v16
	v_mul_f32_e32 v97, v17, v17
	s_waitcnt lgkmcnt(1)
	v_and_b32_e32 v161, 0xffff0000, v24
	v_pk_fma_f32 v[76:77], v[74:75], v[74:75], v[76:77] op_sel_hi:[1,1,0]
	v_pk_fma_f32 v[96:97], v[78:79], v[78:79], v[96:97]
	v_lshlrev_b32_e32 v160, 16, v24
	v_lshlrev_b32_e32 v162, 16, v25
	v_and_b32_e32 v163, 0xffff0000, v25
	s_waitcnt lgkmcnt(0)
	v_lshlrev_b32_e32 v148, 16, v29
	v_lshlrev_b32_e32 v166, 16, v26
	v_and_b32_e32 v168, 0xffff0000, v26
	v_pk_mov_b32 v[24:25], v[26:27], v[30:31] op_sel:[1,0]
	v_mul_f32_e32 v26, v161, v161
	v_pk_add_f32 v[76:77], v[96:97], v[76:77] op_sel:[1,0] op_sel_hi:[0,1]
	v_and_b32_e32 v151, 0xffff0000, v29
	v_mul_f32_e32 v29, v148, v148
	v_lshlrev_b32_e32 v167, 16, v28
	v_and_b32_e32 v169, 0xffff0000, v28
	v_lshlrev_b32_e32 v170, 16, v27
	v_pk_fma_f32 v[26:27], v[160:161], v[160:161], v[26:27] op_sel_hi:[1,1,0]
	v_mul_f32_e32 v28, v163, v163
	v_pk_add_f32 v[76:77], v[96:97], v[76:77]
	v_mul_f32_e32 v96, v151, v151
	v_mov_b32_e32 v27, v29
	v_pk_fma_f32 v[28:29], v[162:163], v[162:163], v[28:29] op_sel_hi:[1,1,0]
	v_and_b32_e32 v173, 0xffff0000, v25
	v_and_b32_e32 v172, 0xffff0000, v24
	v_mul_f32_e32 v24, v168, v168
	v_mul_f32_e32 v25, v169, v169
	v_mov_b32_e32 v29, v96
	v_pk_fma_f32 v[24:25], v[166:167], v[166:167], v[24:25]
	v_pk_add_f32 v[26:27], v[26:27], v[28:29]
	v_and_b32_e32 v155, 0xffff0000, v21
	v_and_b32_e32 v154, 0xffff0000, v20
	v_lshlrev_b32_e32 v171, 16, v30
	v_pk_add_f32 v[24:25], v[24:25], v[26:27]
	v_mul_f32_e32 v26, v172, v172
	v_mul_f32_e32 v27, v173, v173
	v_lshlrev_b32_e32 v18, 16, v19
	v_and_b32_e32 v19, 0xffff0000, v19
	v_lshlrev_b32_e32 v153, 16, v21
	v_lshlrev_b32_e32 v152, 16, v20
	v_mul_f32_e32 v20, v154, v154
	v_mul_f32_e32 v21, v155, v155
	v_and_b32_e32 v159, 0xffff0000, v23
	v_and_b32_e32 v158, 0xffff0000, v22
	v_pk_fma_f32 v[26:27], v[170:171], v[170:171], v[26:27]
	v_pk_fma_f32 v[20:21], v[152:153], v[152:153], v[20:21]
	v_lshlrev_b32_e32 v157, 16, v23
	v_lshlrev_b32_e32 v156, 16, v22
	v_mul_f32_e32 v22, v158, v158
	v_mul_f32_e32 v23, v159, v159
	v_pk_add_f32 v[24:25], v[26:27], v[24:25]
	v_mul_f32_e32 v26, v19, v19
	v_pk_add_f32 v[20:21], v[20:21], v[20:21] op_sel:[0,1] op_sel_hi:[1,0]
	v_pk_fma_f32 v[22:23], v[156:157], v[156:157], v[22:23]
	v_lshlrev_b32_e32 v165, 16, v31
	v_pk_fma_f32 v[26:27], v[18:19], v[18:19], v[26:27] op_sel_hi:[1,1,0]
	v_pk_add_f32 v[20:21], v[22:23], v[20:21]
	v_and_b32_e32 v174, 0xffff0000, v31
	v_mov_b32_e32 v164, v26
	v_mov_b32_e32 v28, v76
	v_mov_b32_e32 v29, v165
	v_mul_f32_e32 v97, v174, v174
	v_pk_add_f32 v[26:27], v[26:27], v[76:77]
	v_mul_f32_e32 v28, v164, v28
	v_mul_f32_e32 v29, v165, v29
	v_pk_add_f32 v[20:21], v[22:23], v[20:21] op_sel:[1,0] op_sel_hi:[0,1]
	v_mov_b32_e32 v27, v29
	v_mov_b32_e32 v21, v97
	v_pk_add_f32 v[20:21], v[26:27], v[20:21]
	global_load_dwordx4 v[96:99], v[68:69], off offset:1280
	global_load_dwordx4 v[100:103], v[70:71], off offset:1280
	global_load_dwordx4 v[104:107], v[72:73], off offset:1280
	v_pk_add_f32 v[20:21], v[20:21], v[24:25]
	s_mov_b32 s74, s73
	v_pk_add_f32 v[20:21], v[20:21], v[20:21] op_sel:[0,1] op_sel_hi:[1,0]
	s_mov_b32 s75, s73
	v_mov_b32_e32 v21, v20
	s_nop 1
	v_permlane32_swap_b32_e32 v20, v21
	v_add_f32_e32 v20, v20, v21
	v_fmamk_f32 v20, v20, 0x3c800000, v185
	v_rsq_f32_e32 v164, v20
	s_mov_b32 s76, s73
	s_mov_b32 s77, s73
	s_mov_b32 s78, s73
	v_mul_f32_e32 v17, v164, v17
	v_mul_f32_e32 v20, v164, v79
	v_cvt_pk_bf16_f32 v68, v20, v17
	v_mul_f32_e32 v17, v164, v74
	v_mul_f32_e32 v20, v164, v75
	v_cvt_pk_bf16_f32 v69, v17, v20
	v_mul_f32_e32 v17, v164, v78
	v_mul_f32_e32 v16, v164, v16
	v_cvt_pk_bf16_f32 v70, v17, v16
	v_mul_f32_e32 v16, v164, v18
	v_mul_f32_e32 v17, v164, v19
	v_cvt_pk_bf16_f32 v71, v16, v17
	v_mul_f32_e32 v152, v164, v152
	v_mfma_f32_32x32x16_bf16 v[64:79], v[68:71], v[64:67], 0
	v_mul_f32_e32 v154, v164, v154
	v_cvt_pk_bf16_f32 v152, v152, v154
	v_mul_f32_e32 v153, v164, v153
	v_mul_f32_e32 v154, v164, v155
	v_cvt_pk_bf16_f32 v153, v153, v154
	v_mul_f32_e32 v154, v164, v156
	v_mul_f32_e32 v155, v164, v158
	v_cvt_pk_bf16_f32 v154, v154, v155
	v_mul_f32_e32 v155, v164, v157
	v_mul_f32_e32 v156, v164, v159
	v_cvt_pk_bf16_f32 v155, v155, v156
	s_mov_b32 s79, s73
	v_mfma_f32_32x32x16_bf16 v[64:79], v[152:155], v[80:83], v[64:79]
	v_mul_f32_e32 v80, v164, v160
	v_mul_f32_e32 v81, v164, v161
	v_cvt_pk_bf16_f32 v80, v80, v81
	v_mul_f32_e32 v81, v164, v162
	v_mul_f32_e32 v82, v164, v163
	v_cvt_pk_bf16_f32 v81, v81, v82
	v_mul_f32_e32 v82, v164, v166
	v_mul_f32_e32 v83, v164, v168
	v_cvt_pk_bf16_f32 v82, v82, v83
	v_mul_f32_e32 v83, v164, v170
	v_mul_f32_e32 v152, v164, v172
	v_cvt_pk_bf16_f32 v83, v83, v152
	s_mov_b32 s80, s73
	v_mfma_f32_32x32x16_bf16 v[64:79], v[80:83], v[84:87], v[64:79]
	v_mul_f32_e32 v80, v164, v167
	v_mul_f32_e32 v81, v164, v169
	v_cvt_pk_bf16_f32 v80, v80, v81
	v_mul_f32_e32 v81, v164, v148
; __device__ __forceinline__ float half_max(float x) { const HalfPair p = half_swap(x); return fmaxf(p.a, p.b); }
; __device__ __forceinline__ int crow(int r, int hi) { return (r & 3) + 8 * (r >> 2) + 4 * hi; }
; __device__ __forceinline__ void swa_mfma(const Params& P, int li, const bf16_t* __restrict__ proj, bf16_t* __restrict__ mix, LAS unsigned char* ldsl) {
;     ...
;                     acc = __builtin_amdgcn_mfma_f32_32x32x16_bf16(as_bf(w), as_bf(qf[d0]), acc, 0, 0, 0); }
; #pragma unroll
;                 for (int r = 0; r < 16; ++r) {
;                     bool valid = true;
;                     if (j == 0) valid = crow(r, hi) > r32;
;                     if (j == 4) valid = crow(r, hi) <= r32;
;                     s[j][r] = valid ? acc[r] : NEG;
;                 }
;             }
;         }
;         float m = sink2;
; #pragma unroll
;         for (int j = 0; j < 5; ++j)
; #pragma unroll
;             for (int r = 0; r < 16; ++r) m = fmaxf(m, s[j][r]);
;         m = half_max(m);
;         float l = 0.f;
; #pragma unroll
;         for (int j = 0; j < 5; ++j)
; #pragma unroll
;             for (int r = 0; r < 16; ++r) { s[j][r] = __builtin_amdgcn_exp2f(s[j][r] - m); l += s[j][r]; }
	v_mul_f32_e32 v82, v164, v151
	v_cvt_pk_bf16_f32 v81, v81, v82
	v_mul_f32_e32 v82, v164, v171
	v_mul_f32_e32 v83, v164, v173
	v_cvt_pk_bf16_f32 v82, v82, v83
	v_mul_f32_e32 v83, v164, v165
	v_mul_f32_e32 v84, v164, v174
	v_cvt_pk_bf16_f32 v83, v83, v84
	s_mov_b32 s81, s73
	v_mfma_f32_32x32x16_bf16 v[64:79], v[80:83], v[88:91], v[64:79]
	s_mov_b32 s82, s73
	s_mov_b32 s83, s73
	s_mov_b32 s84, s73
	s_mov_b32 s85, s73
	s_mov_b32 s86, s73
	s_mov_b32 s87, s73
	v_mov_b64_e32 v[16:17], s[72:73]
	s_nop 4
	v_cndmask_b32_e64 v171, v64, v193, s[0:1]
	v_max3_f32 v64, v147, v146, v145
	v_max3_f32 v64, v64, v144, v143
	v_max3_f32 v64, v64, v142, v141
	v_max3_f32 v64, v64, v140, v139
	v_max3_f32 v64, v64, v138, v137
	v_max3_f32 v64, v64, v136, v135
	v_max3_f32 v64, v64, v134, v133
	v_max3_f32 v64, v64, v119, v117
	v_max3_f32 v64, v64, v0, v1
	v_max3_f32 v64, v64, v2, v3
	v_max3_f32 v64, v64, v4, v5
	v_max3_f32 v64, v64, v6, v7
	v_max3_f32 v64, v64, v8, v9
	v_max3_f32 v64, v64, v10, v11
	v_max3_f32 v64, v64, v12, v13
	v_max3_f32 v64, v64, v14, v15
	v_max3_f32 v64, v64, v32, v33
	v_max3_f32 v64, v64, v34, v35
	v_max3_f32 v64, v64, v36, v37
	v_max3_f32 v64, v64, v38, v39
	v_max3_f32 v64, v64, v40, v41
	v_max3_f32 v64, v64, v42, v43
	v_max3_f32 v64, v64, v44, v45
	v_max3_f32 v64, v64, v46, v47
	v_max3_f32 v64, v64, v48, v49
	v_max3_f32 v64, v64, v50, v51
	v_max3_f32 v64, v64, v52, v53
	v_max3_f32 v64, v64, v54, v55
	v_max3_f32 v64, v64, v56, v57
	v_max3_f32 v64, v64, v58, v59
	v_max3_f32 v64, v64, v60, v61
	v_cndmask_b32_e64 v172, v193, v65, s[4:5]
	v_max3_f32 v64, v64, v62, v63
	v_cndmask_b32_e64 v66, v66, v193, s[6:7]
	v_cndmask_b32_e64 v67, v67, v193, s[8:9]
	v_max3_f32 v64, v64, v171, v172
	v_cndmask_b32_e64 v68, v68, v193, s[10:11]
	v_cndmask_b32_e64 v69, v69, v193, s[12:13]
	v_max3_f32 v64, v64, v66, v67
	v_cndmask_b32_e64 v70, v70, v193, s[14:15]
	v_cndmask_b32_e64 v71, v71, v193, s[16:17]
	v_max3_f32 v64, v64, v68, v69
	v_cndmask_b32_e64 v72, v72, v193, s[18:19]
	v_cndmask_b32_e64 v73, v73, v193, s[20:21]
	v_max3_f32 v64, v64, v70, v71
	v_cndmask_b32_e64 v74, v74, v193, s[22:23]
	v_cndmask_b32_e64 v75, v75, v193, s[24:25]
	v_max3_f32 v64, v64, v72, v73
	v_cndmask_b32_e64 v76, v76, v193, s[26:27]
	v_cndmask_b32_e64 v173, v77, v193, s[28:29]
	v_max3_f32 v64, v64, v74, v75
	v_cndmask_b32_e64 v174, v78, v193, s[30:31]
	v_cndmask_b32_e64 v175, v79, v193, s[34:35]
	v_max3_f32 v64, v64, v76, v173
	v_max3_f32 v64, v64, v174, v175
	v_mov_b32_e32 v65, v64
	s_nop 1
	v_permlane32_swap_b32_e32 v64, v65
	v_max_f32_e32 v65, v65, v65
	v_max_f32_e32 v64, v64, v64
	v_max_f32_e32 v64, v64, v65
	v_sub_f32_e32 v65, v146, v64
	v_exp_f32_e32 v155, v65
	v_sub_f32_e32 v65, v145, v64
	v_exp_f32_e32 v156, v65
	v_sub_f32_e32 v65, v144, v64
	v_exp_f32_e32 v157, v65
	v_sub_f32_e32 v65, v143, v64
	v_exp_f32_e32 v158, v65
	v_sub_f32_e32 v77, v142, v64
	v_add_f32_e32 v65, 0, v155
	v_exp_f32_e32 v159, v77
	v_sub_f32_e32 v77, v141, v64
	v_add_f32_e32 v65, v156, v65
	v_exp_f32_e32 v160, v77
	v_sub_f32_e32 v77, v140, v64
	v_add_f32_e32 v65, v157, v65
	v_exp_f32_e32 v161, v77
	v_sub_f32_e32 v77, v139, v64
	v_add_f32_e32 v65, v158, v65
	v_exp_f32_e32 v163, v77
	v_sub_f32_e32 v77, v138, v64
	v_add_f32_e32 v65, v159, v65
	v_exp_f32_e32 v162, v77
	v_sub_f32_e32 v77, v137, v64
	v_add_f32_e32 v65, v160, v65
	v_exp_f32_e32 v164, v77
	v_sub_f32_e32 v77, v136, v64
	v_add_f32_e32 v65, v161, v65
	v_exp_f32_e32 v165, v77
	v_sub_f32_e32 v77, v135, v64
	v_add_f32_e32 v65, v163, v65
	v_exp_f32_e32 v166, v77
	v_sub_f32_e32 v77, v134, v64
	v_add_f32_e32 v65, v162, v65
	v_exp_f32_e32 v167, v77
	v_sub_f32_e32 v77, v133, v64
	v_add_f32_e32 v65, v164, v65
	v_exp_f32_e32 v168, v77
	v_sub_f32_e32 v77, v119, v64
	v_add_f32_e32 v65, v165, v65
	v_exp_f32_e32 v169, v77
	v_sub_f32_e32 v77, v117, v64
	v_add_f32_e32 v65, v166, v65
	v_exp_f32_e32 v170, v77
	v_sub_f32_e32 v0, v0, v64
	v_add_f32_e32 v65, v167, v65
	v_exp_f32_e32 v136, v0
	v_sub_f32_e32 v0, v1, v64
	v_add_f32_e32 v65, v168, v65
	v_exp_f32_e32 v137, v0
	v_sub_f32_e32 v0, v2, v64
	v_add_f32_e32 v65, v169, v65
	v_exp_f32_e32 v138, v0
	v_sub_f32_e32 v0, v3, v64
	v_add_f32_e32 v65, v170, v65
	v_exp_f32_e32 v139, v0
	v_sub_f32_e32 v1, v4, v64
	v_add_f32_e32 v0, v136, v65
	v_exp_f32_e32 v140, v1
	v_sub_f32_e32 v1, v5, v64
	v_add_f32_e32 v0, v137, v0
	v_exp_f32_e32 v141, v1
	v_sub_f32_e32 v1, v6, v64
	v_add_f32_e32 v0, v138, v0
	v_exp_f32_e32 v142, v1
	v_sub_f32_e32 v1, v7, v64
	v_add_f32_e32 v0, v139, v0
	v_exp_f32_e32 v144, v1
	v_sub_f32_e32 v1, v8, v64
	v_add_f32_e32 v0, v140, v0
	v_exp_f32_e32 v143, v1
	v_sub_f32_e32 v1, v9, v64
	v_add_f32_e32 v0, v141, v0
	v_exp_f32_e32 v145, v1
	v_sub_f32_e32 v1, v10, v64
	v_add_f32_e32 v0, v142, v0
	v_exp_f32_e32 v146, v1
	v_sub_f32_e32 v1, v11, v64
	v_add_f32_e32 v0, v144, v0
	v_exp_f32_e32 v148, v1
	v_sub_f32_e32 v1, v12, v64
	v_add_f32_e32 v0, v143, v0
	v_exp_f32_e32 v151, v1
	v_sub_f32_e32 v1, v13, v64
	v_add_f32_e32 v0, v145, v0
	v_exp_f32_e32 v152, v1
	v_sub_f32_e32 v1, v14, v64
	v_add_f32_e32 v0, v146, v0
	v_exp_f32_e32 v153, v1
	v_sub_f32_e32 v1, v15, v64
	v_add_f32_e32 v0, v148, v0
	v_exp_f32_e32 v154, v1
	v_sub_f32_e32 v1, v32, v64
	v_add_f32_e32 v0, v151, v0
	v_exp_f32_e32 v77, v1
	v_sub_f32_e32 v1, v33, v64
	v_add_f32_e32 v0, v152, v0
	v_exp_f32_e32 v78, v1
	v_sub_f32_e32 v1, v34, v64
	v_add_f32_e32 v0, v153, v0
	v_exp_f32_e32 v79, v1
	v_sub_f32_e32 v1, v35, v64
	v_add_f32_e32 v0, v154, v0
	v_exp_f32_e32 v80, v1
	v_sub_f32_e32 v1, v36, v64
	v_add_f32_e32 v0, v77, v0
	v_exp_f32_e32 v81, v1
	v_sub_f32_e32 v1, v37, v64
	v_add_f32_e32 v0, v78, v0
	v_exp_f32_e32 v82, v1
	v_sub_f32_e32 v1, v38, v64
; __device__ __forceinline__ unsigned pk2(float lo, float hi) { return pg8::cvt_pk_bf16(lo, hi); }
; __device__ __forceinline__ float half_sum(float x) { const HalfPair p = half_swap(x); return p.a + p.b; }
; __device__ __forceinline__ void swa_mfma(const Params& P, int li, const bf16_t* __restrict__ proj, bf16_t* __restrict__ mix, LAS unsigned char* ldsl) {
;     ...
;         float l = 0.f;
; #pragma unroll
;         for (int j = 0; j < 5; ++j)
; #pragma unroll
;             for (int r = 0; r < 16; ++r) { s[j][r] = __builtin_amdgcn_exp2f(s[j][r] - m); l += s[j][r]; }
;         l = half_sum(l);
;         l += __builtin_amdgcn_exp2f(sink2 - m);
;         f32x16 o0, o1;
; #pragma unroll
;         for (int r = 0; r < 16; ++r) { o0[r] = 0.f; o1[r] = 0.f; }
; #pragma unroll
;         for (int j = 0; j < 5; ++j) {
;             const int kb = t0 - 128 + 32 * j;
;             tile_to_lds(vimg, stg, lane);
;             if (j < 4) { const int kn1 = kb + 32; tile_load(stg, kbase + 128 + (size_t)(kn1 < 0 ? 0 : kn1) * 1280, 1280, lane); }
;             if (kb >= 0) {
;                 u32x4 pb[2];
; #pragma unroll
;                 for (int kk = 0; kk < 2; ++kk) { pb[kk].x = pk2(s[j][8 * kk], s[j][8 * kk + 1]); pb[kk].y = pk2(s[j][8 * kk + 2], s[j][8 * kk + 3]);
;                     pb[kk].z = pk2(s[j][8 * kk + 4], s[j][8 * kk + 5]); pb[kk].w = pk2(s[j][8 * kk + 6], s[j][8 * kk + 7]); }
;                 pv_tile_tr(vimg, pb, o0, o1, r32, hi);
	v_add_f32_e32 v0, v79, v0
	v_exp_f32_e32 v83, v1
	v_sub_f32_e32 v1, v39, v64
	v_add_f32_e32 v0, v80, v0
	v_exp_f32_e32 v85, v1
	v_sub_f32_e32 v1, v40, v64
	v_add_f32_e32 v0, v81, v0
	v_exp_f32_e32 v84, v1
	v_sub_f32_e32 v1, v41, v64
	v_add_f32_e32 v0, v82, v0
	v_exp_f32_e32 v86, v1
	v_sub_f32_e32 v1, v42, v64
	v_add_f32_e32 v0, v83, v0
	v_exp_f32_e32 v87, v1
	v_sub_f32_e32 v1, v43, v64
	v_add_f32_e32 v0, v85, v0
	v_exp_f32_e32 v88, v1
	v_sub_f32_e32 v1, v44, v64
	v_add_f32_e32 v0, v84, v0
	v_exp_f32_e32 v91, v1
	v_sub_f32_e32 v1, v45, v64
	v_add_f32_e32 v0, v86, v0
	v_exp_f32_e32 v119, v1
	v_sub_f32_e32 v1, v46, v64
	v_add_f32_e32 v0, v87, v0
	v_exp_f32_e32 v133, v1
	v_sub_f32_e32 v1, v47, v64
	v_add_f32_e32 v0, v88, v0
	v_exp_f32_e32 v135, v1
	v_sub_f32_e32 v1, v48, v64
	v_add_f32_e32 v0, v91, v0
	v_exp_f32_e32 v48, v1
	v_sub_f32_e32 v1, v49, v64
	v_add_f32_e32 v0, v119, v0
	v_exp_f32_e32 v49, v1
	v_sub_f32_e32 v1, v50, v64
	v_add_f32_e32 v0, v133, v0
	v_exp_f32_e32 v50, v1
	v_sub_f32_e32 v1, v51, v64
	v_add_f32_e32 v0, v135, v0
	v_exp_f32_e32 v51, v1
	v_sub_f32_e32 v1, v52, v64
	v_add_f32_e32 v0, v48, v0
	v_exp_f32_e32 v52, v1
	v_sub_f32_e32 v1, v53, v64
	v_add_f32_e32 v0, v49, v0
	v_exp_f32_e32 v53, v1
	v_sub_f32_e32 v1, v54, v64
	v_add_f32_e32 v0, v50, v0
	v_exp_f32_e32 v54, v1
	v_sub_f32_e32 v1, v55, v64
	v_add_f32_e32 v0, v51, v0
	v_exp_f32_e32 v65, v1
	v_add_f32_e32 v0, v52, v0
	v_add_f32_e32 v0, v53, v0
	v_add_f32_e32 v0, v54, v0
	v_add_f32_e32 v4, v65, v0
	v_sub_f32_e32 v0, v56, v64
	v_exp_f32_e32 v55, v0
	v_sub_f32_e32 v0, v57, v64
	v_exp_f32_e32 v56, v0
	v_add_co_u32_e32 v0, vcc, 0x5000, v120
	v_mov_b64_e32 v[18:19], s[74:75]
	s_nop 0
	v_addc_co_u32_e32 v1, vcc, 0, v121, vcc
	global_load_dwordx4 v[32:35], v[120:121], off offset:1280
	global_load_dwordx4 v[36:39], v[0:1], off offset:1280
	v_add_co_u32_e32 v0, vcc, 0xa000, v120
	v_mov_b64_e32 v[20:21], s[76:77]
	s_nop 0
	v_addc_co_u32_e32 v1, vcc, 0, v121, vcc
	v_add_co_u32_e32 v2, vcc, 0xf000, v120
	v_mov_b64_e32 v[22:23], s[78:79]
	s_nop 0
	v_addc_co_u32_e32 v3, vcc, 0, v121, vcc
	global_load_dwordx4 v[40:43], v[0:1], off offset:1280
	global_load_dwordx4 v[44:47], v[2:3], off offset:1280
	v_sub_f32_e32 v0, v58, v64
	v_exp_f32_e32 v89, v0
	v_sub_f32_e32 v0, v59, v64
	v_exp_f32_e32 v90, v0
	v_sub_f32_e32 v1, v60, v64
	v_add_f32_e32 v0, v55, v4
	v_exp_f32_e32 v117, v1
	v_sub_f32_e32 v1, v61, v64
	v_add_f32_e32 v0, v56, v0
	v_exp_f32_e32 v121, v1
	v_sub_f32_e32 v1, v62, v64
	v_add_f32_e32 v0, v89, v0
	v_exp_f32_e32 v120, v1
	v_sub_f32_e32 v1, v63, v64
	v_add_f32_e32 v0, v90, v0
	v_exp_f32_e32 v134, v1
	v_sub_f32_e32 v1, v171, v64
	v_add_f32_e32 v0, v117, v0
	v_exp_f32_e32 v59, v1
	v_sub_f32_e32 v1, v172, v64
	v_add_f32_e32 v0, v121, v0
	v_exp_f32_e32 v61, v1
	v_sub_f32_e32 v1, v66, v64
	v_add_f32_e32 v0, v120, v0
	v_exp_f32_e32 v60, v1
	v_sub_f32_e32 v1, v67, v64
	v_add_f32_e32 v0, v134, v0
	v_exp_f32_e32 v62, v1
	v_sub_f32_e32 v1, v68, v64
	v_add_f32_e32 v0, v59, v0
	v_exp_f32_e32 v63, v1
	v_sub_f32_e32 v1, v69, v64
	v_add_f32_e32 v0, v61, v0
	v_exp_f32_e32 v67, v1
	v_sub_f32_e32 v1, v70, v64
	v_add_f32_e32 v0, v60, v0
	v_exp_f32_e32 v66, v1
	v_sub_f32_e32 v1, v71, v64
	v_add_f32_e32 v0, v62, v0
	v_exp_f32_e32 v69, v1
	v_sub_f32_e32 v1, v72, v64
	v_add_f32_e32 v0, v63, v0
	v_exp_f32_e32 v68, v1
	v_sub_f32_e32 v1, v73, v64
	v_add_f32_e32 v0, v67, v0
	v_exp_f32_e32 v71, v1
	v_sub_f32_e32 v1, v74, v64
	v_add_f32_e32 v0, v66, v0
	v_exp_f32_e32 v70, v1
	v_sub_f32_e32 v1, v75, v64
	v_add_f32_e32 v0, v69, v0
	v_exp_f32_e32 v72, v1
	v_sub_f32_e32 v1, v76, v64
	v_add_f32_e32 v0, v68, v0
	v_exp_f32_e32 v73, v1
	v_sub_f32_e32 v1, v173, v64
	v_add_f32_e32 v0, v71, v0
	v_exp_f32_e32 v75, v1
	v_sub_f32_e32 v1, v174, v64
	v_add_f32_e32 v0, v70, v0
	v_exp_f32_e32 v74, v1
	v_sub_f32_e32 v1, v175, v64
	v_add_f32_e32 v0, v72, v0
	v_exp_f32_e32 v76, v1
	v_add_f32_e32 v0, v73, v0
	v_add_f32_e32 v0, v75, v0
	v_add_f32_e32 v0, v74, v0
	v_add_f32_e32 v57, v76, v0
	v_mov_b64_e32 v[24:25], s[80:81]
	v_mov_b64_e32 v[26:27], s[82:83]
	v_mov_b64_e32 v[28:29], s[84:85]
	v_mov_b64_e32 v[30:31], s[86:87]
	v_mov_b32_e32 v58, v57
	v_mov_b64_e32 v[0:1], v[16:17]
	s_mov_b32 s57, s73
	v_permlane32_swap_b32_e32 v57, v58
	s_andn2_b64 vcc, exec, s[36:37]
	v_mov_b64_e32 v[2:3], v[18:19]
	v_mov_b64_e32 v[4:5], v[20:21]
	v_mov_b64_e32 v[6:7], v[22:23]
	v_mov_b64_e32 v[8:9], v[24:25]
	v_mov_b64_e32 v[10:11], v[26:27]
	v_mov_b64_e32 v[12:13], v[28:29]
	v_mov_b64_e32 v[14:15], v[30:31]
	s_waitcnt vmcnt(7)
	ds_write_b128 v128, v[92:95] offset:4608
	s_waitcnt vmcnt(6)
	ds_write_b128 v128, v[96:99] offset:5760
	s_waitcnt vmcnt(5)
	ds_write_b128 v128, v[100:103] offset:6912
	s_waitcnt vmcnt(4)
	ds_write_b128 v128, v[104:107] offset:8064
	s_cbranch_vccnz .LBB0_225
	v_cvt_pk_bf16_f32 v0, v155, v156
	v_cvt_pk_bf16_f32 v1, v157, v158
	v_cvt_pk_bf16_f32 v2, v159, v160
	v_cvt_pk_bf16_f32 v3, v161, v163
	v_cvt_pk_bf16_f32 v92, v162, v164
	v_cvt_pk_bf16_f32 v93, v165, v166
	v_cvt_pk_bf16_f32 v94, v167, v168
	v_cvt_pk_bf16_f32 v95, v169, v170
	ds_read_b64_tr_b16 v[4:5], v132 offset:4608
	ds_read_b64_tr_b16 v[6:7], v132 offset:5760
	ds_read_b64_tr_b16 v[10:11], v132 offset:5824
	ds_read_b64_tr_b16 v[8:9], v132 offset:4672
	s_waitcnt lgkmcnt(2)
	v_mfma_f32_32x32x16_bf16 v[16:31], v[4:7], v[0:3], 0
	ds_read_b64_tr_b16 v[96:97], v132 offset:6912
	ds_read_b64_tr_b16 v[98:99], v132 offset:8064
	ds_read_b64_tr_b16 v[102:103], v132 offset:8128
	ds_read_b64_tr_b16 v[100:101], v132 offset:6976
	s_waitcnt lgkmcnt(4)
	v_mfma_f32_32x32x16_bf16 v[0:15], v[8:11], v[0:3], 0
	s_waitcnt lgkmcnt(2)
	v_mfma_f32_32x32x16_bf16 v[16:31], v[96:99], v[92:95], v[16:31]
	s_waitcnt lgkmcnt(0)
	v_mfma_f32_32x32x16_bf16 v[0:15], v[100:103], v[92:95], v[0:15]
